# GEMM K-loops: back-edge counter/pointer SALU rotated into previous load-segment tail, plus nop-slot fill and redundant post-barrier wait removal, on the no-setprio version
# baseline (speedup 1.0000x reference)
; #define PG8_STAGE(bufoff, gbase, voff) do { _Pragma("unroll") for (int _i = 0; _i < 2; ++_i) \
;         __builtin_amdgcn_global_load_lds((const unsigned*)((const char*)(gbase) + (voff)[_i]), (PG8_LAS unsigned*)(lds + (bufoff) + ldsw + _i * 8192), 16, 0, 0); } while (0)
; #define PG8_LDA(dst, b, h) do { _Pragma("unroll") for (int m = 0; m < 4; ++m) _Pragma("unroll") for (int k = 0; k < 2; ++k) dst[m][k] = *(const PG8_LAS bf16x8*)(lds + PG8_SA(b, h) + aoff + m * 2048 + k * 1024); } while (0)
; #define PG8_LDB(dst, b, h) do { _Pragma("unroll") for (int n = 0; n < 2; ++n) _Pragma("unroll") for (int k = 0; k < 2; ++k) dst[n][k] = *(const PG8_LAS bf16x8*)(lds + PG8_SB(b, h) + boff + n * 2048 + k * 1024); } while (0)
; #define PG8_SCHED __builtin_amdgcn_sched_barrier(0)
; template <class Epi, class Sched, bool ALIGN_EPI = false, bool SP2 = false>
; __device__ __forceinline__ void gemm_phase(PG8_LAS unsigned char* lds, const Gemm g, const Sched& S, const Epi& E) {
;     ...
;             const bool last = (t == nt - 2);
;             const char* a1 = cA + (size_t)(t + 1) * kstep;
;             const char* a2 = last ? nA : cA + (size_t)(t + 2) * kstep; const char* b2 = last ? nB : cB + (size_t)(t + 2) * kstep;
;             const char* a3 = a2 + kstep; const char* b3 = b2 + kstep;
;             if (last && has_next) S.a_ready(nxt);
;             if constexpr (SP2) {
;             PG8_LDB(B0, 0, 0); PG8_LDB(B1, 0, 1); PG8_SCHED; PG8_LDA(At, 0, 0); PG8_STAGE(PG8_SA(1, 1), a1 + hstep, voffA);
.LBB0_25:
	s_add_i32 s88, 0, 0x10000
	s_add_i32 s90, 0, 0x14000
	ds_read_b128 v[142:145], v200
	ds_read_b128 v[146:149], v200 offset:1024
	ds_read_b128 v[150:153], v200 offset:2048
	ds_read_b128 v[154:157], v200 offset:3072
	ds_read_b128 v[164:167], v200 offset:16384
	ds_read_b128 v[168:171], v200 offset:17408
	ds_read_b128 v[172:175], v200 offset:18432
	ds_read_b128 v[176:179], v200 offset:19456
	s_add_i32 m0, s29, 0xc000
	ds_read_b128 v[180:183], v141
	ds_read_b128 v[184:187], v141 offset:1024
	ds_read_b128 v[188:191], v141 offset:2048
	ds_read_b128 v[192:195], v141 offset:3072
	ds_read_b128 v[196:199], v141 offset:4096
	ds_read_b128 v[222:225], v141 offset:5120
	ds_read_b128 v[226:229], v141 offset:6144
	global_load_lds_dwordx4 v134, s[80:81]
	s_add_i32 m0, s29, 0xe000
	ds_read_b128 v[230:233], v141 offset:7168
	global_load_lds_dwordx4 v136, s[80:81]
	s_add_u32 s4, s80, 0xfff80080
	s_addc_u32 s5, s81, -1
	s_cmp_eq_u32 s87, 28
	s_cselect_b32 s53, s55, s5
	s_cselect_b32 s52, s83, s4
	s_cselect_b32 s5, s73, s86
	s_cselect_b32 s4, s84, s85

; #define PG8_STAGE(bufoff, gbase, voff) do { _Pragma("unroll") for (int _i = 0; _i < 2; ++_i) \
;         __builtin_amdgcn_global_load_lds((const unsigned*)((const char*)(gbase) + (voff)[_i]), (PG8_LAS unsigned*)(lds + (bufoff) + ldsw + _i * 8192), 16, 0, 0); } while (0)
; #define PG8_LDA(dst, b, h) do { _Pragma("unroll") for (int m = 0; m < 4; ++m) _Pragma("unroll") for (int k = 0; k < 2; ++k) dst[m][k] = *(const PG8_LAS bf16x8*)(lds + PG8_SA(b, h) + aoff + m * 2048 + k * 1024); } while (0)
; #define PG8_LDB(dst, b, h) do { _Pragma("unroll") for (int n = 0; n < 2; ++n) _Pragma("unroll") for (int k = 0; k < 2; ++k) dst[n][k] = *(const PG8_LAS bf16x8*)(lds + PG8_SB(b, h) + boff + n * 2048 + k * 1024); } while (0)
; #define PG8_MMA(ai, bj, At, Bt) do { __builtin_amdgcn_s_setprio(1); _Pragma("unroll") for (int m = 0; m < 4; ++m) _Pragma("unroll") for (int n = 0; n < 2; ++n) _Pragma("unroll") for (int k = 0; k < 2; ++k) \
;         acc[ai][bj][m][n] = __builtin_amdgcn_mfma_f32_16x16x32_bf16(Bt[n][k], At[m][k], acc[ai][bj][m][n], 0, 0, 0); __builtin_amdgcn_s_setprio(0); } while (0)
; #define PG8_WAIT_V(n) asm volatile("s_waitcnt vmcnt(" #n ")" ::: "memory")
; #define PG8_WAIT_L(n) asm volatile("s_waitcnt lgkmcnt(" #n ")" ::: "memory")
; #define PG8_BAR __builtin_amdgcn_s_barrier()
; #define PG8_SCHED __builtin_amdgcn_sched_barrier(0)
; template <class Epi, class Sched, bool ALIGN_EPI = false, bool SP2 = false>
; __device__ __forceinline__ void gemm_phase(PG8_LAS unsigned char* lds, const Gemm g, const Sched& S, const Epi& E) {
;     ...
;             PG8_LDB(B0, 0, 0); PG8_LDB(B1, 0, 1); PG8_SCHED; PG8_LDA(At, 0, 0); PG8_STAGE(PG8_SA(1, 1), a1 + hstep, voffA);
;             PG8_WAIT_V(8); PG8_WAIT_L(0); PG8_BAR; PG8_MMA(0, 0, At, B0); PG8_MMA(0, 1, At, B1); PG8_BAR; PG8_SCHED;
;             PG8_LDA(At, 0, 1); PG8_STAGE(PG8_SB(0, 0), b2, voffB); PG8_STAGE(PG8_SB(0, 1), b2 + hstep, voffB); PG8_STAGE(PG8_SA(0, 0), a2, voffA);
	s_waitcnt vmcnt(8)
	s_waitcnt lgkmcnt(0)
	s_barrier
	v_mfma_f32_16x16x32_bf16 v[124:127], v[142:145], v[180:183], v[124:127]
	v_mfma_f32_16x16x32_bf16 v[120:123], v[150:153], v[180:183], v[120:123]
	v_mfma_f32_16x16x32_bf16 v[116:119], v[142:145], v[188:191], v[116:119]
	v_mfma_f32_16x16x32_bf16 v[112:115], v[150:153], v[188:191], v[112:115]
	v_mfma_f32_16x16x32_bf16 v[100:103], v[142:145], v[196:199], v[100:103]
	v_mfma_f32_16x16x32_bf16 v[96:99], v[150:153], v[196:199], v[96:99]
	v_mfma_f32_16x16x32_bf16 v[84:87], v[142:145], v[226:229], v[84:87]
	v_mfma_f32_16x16x32_bf16 v[80:83], v[150:153], v[226:229], v[80:83]
	v_mfma_f32_16x16x32_bf16 v[124:127], v[146:149], v[184:187], v[124:127]
	v_mfma_f32_16x16x32_bf16 v[120:123], v[154:157], v[184:187], v[120:123]
	v_mfma_f32_16x16x32_bf16 v[116:119], v[146:149], v[192:195], v[116:119]
	v_mfma_f32_16x16x32_bf16 v[112:115], v[154:157], v[192:195], v[112:115]
	v_mfma_f32_16x16x32_bf16 v[100:103], v[146:149], v[222:225], v[100:103]
	v_mfma_f32_16x16x32_bf16 v[96:99], v[154:157], v[222:225], v[96:99]
	v_mfma_f32_16x16x32_bf16 v[84:87], v[146:149], v[230:233], v[84:87]
	v_mfma_f32_16x16x32_bf16 v[80:83], v[154:157], v[230:233], v[80:83]
	v_mfma_f32_16x16x32_bf16 v[108:111], v[164:167], v[180:183], v[108:111]
	v_mfma_f32_16x16x32_bf16 v[104:107], v[172:175], v[180:183], v[104:107]
	v_mfma_f32_16x16x32_bf16 v[92:95], v[164:167], v[188:191], v[92:95]
	v_mfma_f32_16x16x32_bf16 v[88:91], v[172:175], v[188:191], v[88:91]
	v_mfma_f32_16x16x32_bf16 v[76:79], v[164:167], v[196:199], v[76:79]
	v_mfma_f32_16x16x32_bf16 v[72:75], v[172:175], v[196:199], v[72:75]
	v_mfma_f32_16x16x32_bf16 v[68:71], v[164:167], v[226:229], v[68:71]
	v_mfma_f32_16x16x32_bf16 v[64:67], v[172:175], v[226:229], v[64:67]
	v_mfma_f32_16x16x32_bf16 v[108:111], v[168:171], v[184:187], v[108:111]
	v_mfma_f32_16x16x32_bf16 v[104:107], v[176:179], v[184:187], v[104:107]
	v_mfma_f32_16x16x32_bf16 v[92:95], v[168:171], v[192:195], v[92:95]
	v_mfma_f32_16x16x32_bf16 v[88:91], v[176:179], v[192:195], v[88:91]
	v_mfma_f32_16x16x32_bf16 v[76:79], v[168:171], v[222:225], v[76:79]
	v_mfma_f32_16x16x32_bf16 v[72:75], v[176:179], v[222:225], v[72:75]
	v_mfma_f32_16x16x32_bf16 v[68:71], v[168:171], v[230:233], v[68:71]
	v_mfma_f32_16x16x32_bf16 v[64:67], v[176:179], v[230:233], v[64:67]
	s_barrier
	s_add_i32 s88, s88, s28
	s_mov_b32 m0, s88
	ds_read_b128 v[180:183], v141 offset:16384
	ds_read_b128 v[184:187], v141 offset:17408
	ds_read_b128 v[188:191], v141 offset:18432
	ds_read_b128 v[192:195], v141 offset:19456
	global_load_lds_dwordx4 v160, s[4:5]
	s_add_i32 m0, s88, 0x2000
	s_add_u32 s88, s4, 0x80000
	s_addc_u32 s89, s5, 0
	s_add_i32 s90, s90, s28
	global_load_lds_dwordx4 v128, s[4:5]
	s_mov_b32 m0, s90
	ds_read_b128 v[196:199], v141 offset:20480
	global_load_lds_dwordx4 v160, s[88:89]
	s_add_i32 m0, s90, 0x2000
	ds_read_b128 v[222:225], v141 offset:21504
	global_load_lds_dwordx4 v128, s[88:89]
	s_mov_b32 m0, s29
	ds_read_b128 v[226:229], v141 offset:22528
	global_load_lds_dwordx4 v132, s[52:53]
	s_mov_b32 m0, s45
	ds_read_b128 v[230:233], v141 offset:23552
	global_load_lds_dwordx4 v130, s[52:53]
	s_add_u32 s98, s52, 0x80
	s_addc_u32 s99, s53, 0


; #define PG8_STAGE(bufoff, gbase, voff) do { _Pragma("unroll") for (int _i = 0; _i < 2; ++_i) \
;         __builtin_amdgcn_global_load_lds((const unsigned*)((const char*)(gbase) + (voff)[_i]), (PG8_LAS unsigned*)(lds + (bufoff) + ldsw + _i * 8192), 16, 0, 0); } while (0)
; #define PG8_LDA(dst, b, h) do { _Pragma("unroll") for (int m = 0; m < 4; ++m) _Pragma("unroll") for (int k = 0; k < 2; ++k) dst[m][k] = *(const PG8_LAS bf16x8*)(lds + PG8_SA(b, h) + aoff + m * 2048 + k * 1024); } while (0)
; #define PG8_LDB(dst, b, h) do { _Pragma("unroll") for (int n = 0; n < 2; ++n) _Pragma("unroll") for (int k = 0; k < 2; ++k) dst[n][k] = *(const PG8_LAS bf16x8*)(lds + PG8_SB(b, h) + boff + n * 2048 + k * 1024); } while (0)
; #define PG8_MMA(ai, bj, At, Bt) do { __builtin_amdgcn_s_setprio(1); _Pragma("unroll") for (int m = 0; m < 4; ++m) _Pragma("unroll") for (int n = 0; n < 2; ++n) _Pragma("unroll") for (int k = 0; k < 2; ++k) \
;         acc[ai][bj][m][n] = __builtin_amdgcn_mfma_f32_16x16x32_bf16(Bt[n][k], At[m][k], acc[ai][bj][m][n], 0, 0, 0); __builtin_amdgcn_s_setprio(0); } while (0)
; #define PG8_WAIT_V(n) asm volatile("s_waitcnt vmcnt(" #n ")" ::: "memory")
; #define PG8_WAIT_L(n) asm volatile("s_waitcnt lgkmcnt(" #n ")" ::: "memory")
; #define PG8_BAR __builtin_amdgcn_s_barrier()
; #define PG8_SCHED __builtin_amdgcn_sched_barrier(0)
; template <class Epi, class Sched, bool ALIGN_EPI = false, bool SP2 = false>
; __device__ __forceinline__ void gemm_phase(PG8_LAS unsigned char* lds, const Gemm g, const Sched& S, const Epi& E) {
;     ...
;             PG8_WAIT_V(8); PG8_WAIT_L(0); PG8_BAR; PG8_MMA(1, 0, At, B0); PG8_MMA(1, 1, At, B1); PG8_BAR; PG8_SCHED;
;             PG8_LDB(B0, 1, 0); PG8_LDB(B1, 1, 1); PG8_SCHED; PG8_LDA(At, 1, 0); PG8_STAGE(PG8_SA(0, 1), a2 + hstep, voffA);
	s_waitcnt vmcnt(8)
	s_waitcnt lgkmcnt(0)
	s_barrier
	v_mfma_f32_16x16x32_bf16 v[60:63], v[142:145], v[180:183], v[60:63]
	v_mfma_f32_16x16x32_bf16 v[56:59], v[150:153], v[180:183], v[56:59]
	v_mfma_f32_16x16x32_bf16 v[52:55], v[142:145], v[188:191], v[52:55]
	v_mfma_f32_16x16x32_bf16 v[48:51], v[150:153], v[188:191], v[48:51]
	v_mfma_f32_16x16x32_bf16 v[36:39], v[142:145], v[196:199], v[36:39]
	v_mfma_f32_16x16x32_bf16 v[32:35], v[150:153], v[196:199], v[32:35]
	v_mfma_f32_16x16x32_bf16 v[20:23], v[142:145], v[226:229], v[20:23]
	v_mfma_f32_16x16x32_bf16 v[16:19], v[150:153], v[226:229], v[16:19]
	v_mfma_f32_16x16x32_bf16 v[60:63], v[146:149], v[184:187], v[60:63]
	v_mfma_f32_16x16x32_bf16 v[56:59], v[154:157], v[184:187], v[56:59]
	v_mfma_f32_16x16x32_bf16 v[52:55], v[146:149], v[192:195], v[52:55]
	v_mfma_f32_16x16x32_bf16 v[48:51], v[154:157], v[192:195], v[48:51]
	v_mfma_f32_16x16x32_bf16 v[36:39], v[146:149], v[222:225], v[36:39]
	v_mfma_f32_16x16x32_bf16 v[32:35], v[154:157], v[222:225], v[32:35]
	v_mfma_f32_16x16x32_bf16 v[20:23], v[146:149], v[230:233], v[20:23]
	v_mfma_f32_16x16x32_bf16 v[16:19], v[154:157], v[230:233], v[16:19]
	v_mfma_f32_16x16x32_bf16 v[44:47], v[164:167], v[180:183], v[44:47]
	v_mfma_f32_16x16x32_bf16 v[40:43], v[172:175], v[180:183], v[40:43]
	v_mfma_f32_16x16x32_bf16 v[28:31], v[164:167], v[188:191], v[28:31]
	v_mfma_f32_16x16x32_bf16 v[24:27], v[172:175], v[188:191], v[24:27]
	v_mfma_f32_16x16x32_bf16 v[12:15], v[164:167], v[196:199], v[12:15]
	v_mfma_f32_16x16x32_bf16 v[8:11], v[172:175], v[196:199], v[8:11]
	v_mfma_f32_16x16x32_bf16 v[4:7], v[164:167], v[226:229], v[4:7]
	v_mfma_f32_16x16x32_bf16 v[0:3], v[172:175], v[226:229], v[0:3]
	v_mfma_f32_16x16x32_bf16 v[44:47], v[168:171], v[184:187], v[44:47]
	v_mfma_f32_16x16x32_bf16 v[40:43], v[176:179], v[184:187], v[40:43]
	v_mfma_f32_16x16x32_bf16 v[28:31], v[168:171], v[192:195], v[28:31]
	v_mfma_f32_16x16x32_bf16 v[24:27], v[176:179], v[192:195], v[24:27]
	v_mfma_f32_16x16x32_bf16 v[12:15], v[168:171], v[222:225], v[12:15]
	v_mfma_f32_16x16x32_bf16 v[8:11], v[176:179], v[222:225], v[8:11]
	v_mfma_f32_16x16x32_bf16 v[4:7], v[168:171], v[230:233], v[4:7]
	v_mfma_f32_16x16x32_bf16 v[0:3], v[176:179], v[230:233], v[0:3]
	s_barrier
	s_add_i32 s88, 0, 0x18000
	s_add_i32 s89, 0, 0x1c000
	ds_read_b128 v[142:145], v200 offset:32768
	ds_read_b128 v[146:149], v200 offset:33792
	ds_read_b128 v[150:153], v200 offset:34816
	ds_read_b128 v[154:157], v200 offset:35840
	ds_read_b128 v[164:167], v200 offset:49152
	ds_read_b128 v[168:171], v200 offset:50176
	ds_read_b128 v[172:175], v200 offset:51200
	ds_read_b128 v[176:179], v200 offset:52224
	s_add_u32 s52, s52, 0x80000
	s_addc_u32 s53, s53, 0
	s_mov_b32 m0, s56
	ds_read_b128 v[180:183], v141 offset:32768
	ds_read_b128 v[184:187], v141 offset:33792
	ds_read_b128 v[188:191], v141 offset:34816
	ds_read_b128 v[192:195], v141 offset:35840
	ds_read_b128 v[196:199], v141 offset:36864
	ds_read_b128 v[222:225], v141 offset:37888
	ds_read_b128 v[226:229], v141 offset:38912
	global_load_lds_dwordx4 v132, s[52:53]
	s_mov_b32 m0, s57
	ds_read_b128 v[230:233], v141 offset:39936
	global_load_lds_dwordx4 v130, s[52:53]

; #define PG8_STAGE(bufoff, gbase, voff) do { _Pragma("unroll") for (int _i = 0; _i < 2; ++_i) \
;         __builtin_amdgcn_global_load_lds((const unsigned*)((const char*)(gbase) + (voff)[_i]), (PG8_LAS unsigned*)(lds + (bufoff) + ldsw + _i * 8192), 16, 0, 0); } while (0)
; #define PG8_LDA(dst, b, h) do { _Pragma("unroll") for (int m = 0; m < 4; ++m) _Pragma("unroll") for (int k = 0; k < 2; ++k) dst[m][k] = *(const PG8_LAS bf16x8*)(lds + PG8_SA(b, h) + aoff + m * 2048 + k * 1024); } while (0)
; #define PG8_MMA(ai, bj, At, Bt) do { __builtin_amdgcn_s_setprio(1); _Pragma("unroll") for (int m = 0; m < 4; ++m) _Pragma("unroll") for (int n = 0; n < 2; ++n) _Pragma("unroll") for (int k = 0; k < 2; ++k) \
;         acc[ai][bj][m][n] = __builtin_amdgcn_mfma_f32_16x16x32_bf16(Bt[n][k], At[m][k], acc[ai][bj][m][n], 0, 0, 0); __builtin_amdgcn_s_setprio(0); } while (0)
; #define PG8_WAIT_V(n) asm volatile("s_waitcnt vmcnt(" #n ")" ::: "memory")
; #define PG8_WAIT_L(n) asm volatile("s_waitcnt lgkmcnt(" #n ")" ::: "memory")
; #define PG8_BAR __builtin_amdgcn_s_barrier()
; #define PG8_SCHED __builtin_amdgcn_sched_barrier(0)
; template <class Epi, class Sched, bool ALIGN_EPI = false, bool SP2 = false>
; __device__ __forceinline__ void gemm_phase(PG8_LAS unsigned char* lds, const Gemm g, const Sched& S, const Epi& E) {
;     ...
;             PG8_WAIT_V(8); PG8_WAIT_L(0); PG8_BAR; PG8_MMA(0, 0, At, B0); PG8_MMA(0, 1, At, B1); PG8_BAR; PG8_SCHED;
;             PG8_LDA(At, 1, 1); PG8_STAGE(PG8_SB(1, 0), b3, voffB); PG8_STAGE(PG8_SB(1, 1), b3 + hstep, voffB); PG8_STAGE(PG8_SA(1, 0), a3, voffA);
	s_waitcnt vmcnt(8)
	s_waitcnt lgkmcnt(0)
	s_barrier
	v_mfma_f32_16x16x32_bf16 v[124:127], v[142:145], v[180:183], v[124:127]
	v_mfma_f32_16x16x32_bf16 v[120:123], v[150:153], v[180:183], v[120:123]
	v_mfma_f32_16x16x32_bf16 v[116:119], v[142:145], v[188:191], v[116:119]
	v_mfma_f32_16x16x32_bf16 v[112:115], v[150:153], v[188:191], v[112:115]
	v_mfma_f32_16x16x32_bf16 v[100:103], v[142:145], v[196:199], v[100:103]
	v_mfma_f32_16x16x32_bf16 v[96:99], v[150:153], v[196:199], v[96:99]
	v_mfma_f32_16x16x32_bf16 v[84:87], v[142:145], v[226:229], v[84:87]
	v_mfma_f32_16x16x32_bf16 v[80:83], v[150:153], v[226:229], v[80:83]
	v_mfma_f32_16x16x32_bf16 v[124:127], v[146:149], v[184:187], v[124:127]
	v_mfma_f32_16x16x32_bf16 v[120:123], v[154:157], v[184:187], v[120:123]
	v_mfma_f32_16x16x32_bf16 v[116:119], v[146:149], v[192:195], v[116:119]
	v_mfma_f32_16x16x32_bf16 v[112:115], v[154:157], v[192:195], v[112:115]
	v_mfma_f32_16x16x32_bf16 v[100:103], v[146:149], v[222:225], v[100:103]
	v_mfma_f32_16x16x32_bf16 v[96:99], v[154:157], v[222:225], v[96:99]
	v_mfma_f32_16x16x32_bf16 v[84:87], v[146:149], v[230:233], v[84:87]
	v_mfma_f32_16x16x32_bf16 v[80:83], v[154:157], v[230:233], v[80:83]
	v_mfma_f32_16x16x32_bf16 v[108:111], v[164:167], v[180:183], v[108:111]
	v_mfma_f32_16x16x32_bf16 v[104:107], v[172:175], v[180:183], v[104:107]
	v_mfma_f32_16x16x32_bf16 v[92:95], v[164:167], v[188:191], v[92:95]
	v_mfma_f32_16x16x32_bf16 v[88:91], v[172:175], v[188:191], v[88:91]
	v_mfma_f32_16x16x32_bf16 v[76:79], v[164:167], v[196:199], v[76:79]
	v_mfma_f32_16x16x32_bf16 v[72:75], v[172:175], v[196:199], v[72:75]
	v_mfma_f32_16x16x32_bf16 v[68:71], v[164:167], v[226:229], v[68:71]
	v_mfma_f32_16x16x32_bf16 v[64:67], v[172:175], v[226:229], v[64:67]
	v_mfma_f32_16x16x32_bf16 v[108:111], v[168:171], v[184:187], v[108:111]
	v_mfma_f32_16x16x32_bf16 v[104:107], v[176:179], v[184:187], v[104:107]
	v_mfma_f32_16x16x32_bf16 v[92:95], v[168:171], v[192:195], v[92:95]
	v_mfma_f32_16x16x32_bf16 v[88:91], v[176:179], v[192:195], v[88:91]
	v_mfma_f32_16x16x32_bf16 v[76:79], v[168:171], v[222:225], v[76:79]
	v_mfma_f32_16x16x32_bf16 v[72:75], v[176:179], v[222:225], v[72:75]
	v_mfma_f32_16x16x32_bf16 v[68:71], v[168:171], v[230:233], v[68:71]
	v_mfma_f32_16x16x32_bf16 v[64:67], v[176:179], v[230:233], v[64:67]
	s_barrier
	s_add_i32 s52, s88, s28
	s_mov_b32 m0, s52
	ds_read_b128 v[180:183], v141 offset:49152
	ds_read_b128 v[184:187], v141 offset:50176
	ds_read_b128 v[188:191], v141 offset:51200
	ds_read_b128 v[192:195], v141 offset:52224
	s_add_u32 s4, s4, 0x80
	s_addc_u32 s5, s5, 0
	global_load_lds_dwordx4 v160, s[4:5]
	s_add_i32 m0, s52, 0x2000
	s_add_i32 s52, s89, s28
	global_load_lds_dwordx4 v128, s[4:5]
	s_add_u32 s4, s4, 0x80000
	s_addc_u32 s5, s5, 0
	s_mov_b32 m0, s52
	ds_read_b128 v[196:199], v141 offset:53248
	global_load_lds_dwordx4 v160, s[4:5]
	s_add_i32 m0, s52, 0x2000
	ds_read_b128 v[222:225], v141 offset:54272
	global_load_lds_dwordx4 v128, s[4:5]
	s_mov_b32 m0, s24
	ds_read_b128 v[226:229], v141 offset:55296
	global_load_lds_dwordx4 v132, s[98:99]
	s_mov_b32 m0, s59
	ds_read_b128 v[230:233], v141 offset:56320
	global_load_lds_dwordx4 v130, s[98:99]


; #define PG8_STAGE(bufoff, gbase, voff) do { _Pragma("unroll") for (int _i = 0; _i < 2; ++_i) \
;         __builtin_amdgcn_global_load_lds((const unsigned*)((const char*)(gbase) + (voff)[_i]), (PG8_LAS unsigned*)(lds + (bufoff) + ldsw + _i * 8192), 16, 0, 0); } while (0)
; #define PG8_LDA(dst, b, h) do { _Pragma("unroll") for (int m = 0; m < 4; ++m) _Pragma("unroll") for (int k = 0; k < 2; ++k) dst[m][k] = *(const PG8_LAS bf16x8*)(lds + PG8_SA(b, h) + aoff + m * 2048 + k * 1024); } while (0)
; #define PG8_LDB(dst, b, h) do { _Pragma("unroll") for (int n = 0; n < 2; ++n) _Pragma("unroll") for (int k = 0; k < 2; ++k) dst[n][k] = *(const PG8_LAS bf16x8*)(lds + PG8_SB(b, h) + boff + n * 2048 + k * 1024); } while (0)
; template <class Epi, class Sched, bool ALIGN_EPI = false, bool SP2 = false>
; __device__ __forceinline__ void gemm_phase(PG8_LAS unsigned char* lds, const Gemm g, const Sched& S, const Epi& E) {
;     ...
;             PG8_WAIT_V(8); PG8_WAIT_L(0); PG8_BAR; PG8_MMA(1, 0, At, B0); PG8_MMA(1, 1, At, B1); PG8_BAR; PG8_SCHED;
;             } else {
;             PG8_LDB(B0, 0, 0); PG8_SCHED; PG8_LDA(At, 0, 0); PG8_STAGE(PG8_SA(1, 1), a1 + hstep, voffA);
;             PG8_WAIT_L(8); PG8_BAR; PG8_WAIT_L(0); PG8_MMA(0, 0, At, B0); PG8_BAR; PG8_SCHED;
;             PG8_LDB(B1, 0, 1); PG8_STAGE(PG8_SB(0, 0), b2, voffB);
;             PG8_BAR; PG8_WAIT_L(0); PG8_MMA(0, 1, At, B1); PG8_BAR;
;             PG8_LDA(At, 0, 1); PG8_STAGE(PG8_SA(0, 0), a2, voffA);
;             PG8_BAR; PG8_WAIT_L(0); PG8_MMA(1, 0, At, B0); PG8_BAR; PG8_SCHED;
;             PG8_STAGE(PG8_SB(0, 1), b2 + hstep, voffB);
;             PG8_WAIT_V(6); PG8_BAR; PG8_MMA(1, 1, At, B1); PG8_BAR;
;             PG8_LDB(B0, 1, 0); PG8_SCHED; PG8_LDA(At, 1, 0); PG8_STAGE(PG8_SA(0, 1), a2 + hstep, voffA);
;             PG8_WAIT_L(8); PG8_BAR; PG8_WAIT_L(0); PG8_MMA(0, 0, At, B0); PG8_BAR; PG8_SCHED;
;             PG8_LDB(B1, 1, 1); PG8_STAGE(PG8_SB(1, 0), b3, voffB);
;             PG8_BAR; PG8_WAIT_L(0); PG8_MMA(0, 1, At, B1); PG8_BAR;
;             PG8_LDA(At, 1, 1); PG8_STAGE(PG8_SA(1, 0), a3, voffA);
;             PG8_BAR; PG8_WAIT_L(0); PG8_MMA(1, 0, At, B0); PG8_BAR; PG8_SCHED;
;             PG8_STAGE(PG8_SB(1, 1), b3 + hstep, voffB);
;             PG8_WAIT_V(6); PG8_BAR; PG8_MMA(1, 1, At, B1); PG8_BAR;
;             }
;         }
;         if constexpr (ALIGN_EPI) { if (wr == 0) PG8_BAR; }
	s_add_i32 s87, s87, 2
	s_add_u32 s80, s80, 0x100
	s_addc_u32 s81, s81, 0
	s_add_u32 s85, s85, 0x100
	s_addc_u32 s86, s86, 0
	s_waitcnt vmcnt(8)
	s_waitcnt lgkmcnt(0)
	s_barrier
	v_mfma_f32_16x16x32_bf16 v[60:63], v[142:145], v[180:183], v[60:63]
	v_mfma_f32_16x16x32_bf16 v[56:59], v[150:153], v[180:183], v[56:59]
	v_mfma_f32_16x16x32_bf16 v[52:55], v[142:145], v[188:191], v[52:55]
	v_mfma_f32_16x16x32_bf16 v[48:51], v[150:153], v[188:191], v[48:51]
	v_mfma_f32_16x16x32_bf16 v[36:39], v[142:145], v[196:199], v[36:39]
	v_mfma_f32_16x16x32_bf16 v[32:35], v[150:153], v[196:199], v[32:35]
	v_mfma_f32_16x16x32_bf16 v[20:23], v[142:145], v[226:229], v[20:23]
	v_mfma_f32_16x16x32_bf16 v[16:19], v[150:153], v[226:229], v[16:19]
	v_mfma_f32_16x16x32_bf16 v[60:63], v[146:149], v[184:187], v[60:63]
	v_mfma_f32_16x16x32_bf16 v[56:59], v[154:157], v[184:187], v[56:59]
	v_mfma_f32_16x16x32_bf16 v[52:55], v[146:149], v[192:195], v[52:55]
	v_mfma_f32_16x16x32_bf16 v[48:51], v[154:157], v[192:195], v[48:51]
	v_mfma_f32_16x16x32_bf16 v[36:39], v[146:149], v[222:225], v[36:39]
	v_mfma_f32_16x16x32_bf16 v[32:35], v[154:157], v[222:225], v[32:35]
	v_mfma_f32_16x16x32_bf16 v[20:23], v[146:149], v[230:233], v[20:23]
	v_mfma_f32_16x16x32_bf16 v[16:19], v[154:157], v[230:233], v[16:19]
	v_mfma_f32_16x16x32_bf16 v[44:47], v[164:167], v[180:183], v[44:47]
	v_mfma_f32_16x16x32_bf16 v[40:43], v[172:175], v[180:183], v[40:43]
	v_mfma_f32_16x16x32_bf16 v[28:31], v[164:167], v[188:191], v[28:31]
	v_mfma_f32_16x16x32_bf16 v[24:27], v[172:175], v[188:191], v[24:27]
	v_mfma_f32_16x16x32_bf16 v[12:15], v[164:167], v[196:199], v[12:15]
	v_mfma_f32_16x16x32_bf16 v[8:11], v[172:175], v[196:199], v[8:11]
	v_mfma_f32_16x16x32_bf16 v[4:7], v[164:167], v[226:229], v[4:7]
	v_mfma_f32_16x16x32_bf16 v[0:3], v[172:175], v[226:229], v[0:3]
	v_mfma_f32_16x16x32_bf16 v[44:47], v[168:171], v[184:187], v[44:47]
	v_mfma_f32_16x16x32_bf16 v[40:43], v[176:179], v[184:187], v[40:43]
	v_mfma_f32_16x16x32_bf16 v[28:31], v[168:171], v[192:195], v[28:31]
	v_mfma_f32_16x16x32_bf16 v[24:27], v[176:179], v[192:195], v[24:27]
	v_mfma_f32_16x16x32_bf16 v[12:15], v[168:171], v[222:225], v[12:15]
	v_mfma_f32_16x16x32_bf16 v[8:11], v[176:179], v[222:225], v[8:11]
	v_mfma_f32_16x16x32_bf16 v[4:7], v[168:171], v[230:233], v[4:7]
	v_mfma_f32_16x16x32_bf16 v[0:3], v[176:179], v[230:233], v[0:3]
	s_barrier
	s_cmp_gt_u32 s87, 29
	s_cbranch_scc0 .LBB0_25
	s_and_b64 vcc, exec, s[42:43]
	s_cbranch_vccz .LBB0_28
	s_barrier

; #define PG8_STAGE(bufoff, gbase, voff) do { _Pragma("unroll") for (int _i = 0; _i < 2; ++_i) \
;         __builtin_amdgcn_global_load_lds((const unsigned*)((const char*)(gbase) + (voff)[_i]), (PG8_LAS unsigned*)(lds + (bufoff) + ldsw + _i * 8192), 16, 0, 0); } while (0)
; #define PG8_LDA(dst, b, h) do { _Pragma("unroll") for (int m = 0; m < 4; ++m) _Pragma("unroll") for (int k = 0; k < 2; ++k) dst[m][k] = *(const PG8_LAS bf16x8*)(lds + PG8_SA(b, h) + aoff + m * 2048 + k * 1024); } while (0)
; #define PG8_LDB(dst, b, h) do { _Pragma("unroll") for (int n = 0; n < 2; ++n) _Pragma("unroll") for (int k = 0; k < 2; ++k) dst[n][k] = *(const PG8_LAS bf16x8*)(lds + PG8_SB(b, h) + boff + n * 2048 + k * 1024); } while (0)
; #define PG8_SCHED __builtin_amdgcn_sched_barrier(0)
; template <class Epi, class Sched, bool ALIGN_EPI = false, bool SP2 = false>
; __device__ __forceinline__ void gemm_phase(PG8_LAS unsigned char* lds, const Gemm g, const Sched& S, const Epi& E) {
;     ...
;             const bool last = (t == nt - 2);
;             const char* a1 = cA + (size_t)(t + 1) * kstep;
;             const char* a2 = last ? nA : cA + (size_t)(t + 2) * kstep; const char* b2 = last ? nB : cB + (size_t)(t + 2) * kstep;
;             const char* a3 = a2 + kstep; const char* b3 = b2 + kstep;
;             if (last && has_next) S.a_ready(nxt);
;             if constexpr (SP2) {
;             PG8_LDB(B0, 0, 0); PG8_LDB(B1, 0, 1); PG8_SCHED; PG8_LDA(At, 0, 0); PG8_STAGE(PG8_SA(1, 1), a1 + hstep, voffA);
.LBB0_52:
	s_add_i32 s84, 0, 0x10000
	s_add_i32 s85, 0, 0x14000
	ds_read_b128 v[142:145], v200
	ds_read_b128 v[146:149], v200 offset:1024
	ds_read_b128 v[150:153], v200 offset:2048
	ds_read_b128 v[154:157], v200 offset:3072
	ds_read_b128 v[164:167], v200 offset:16384
	ds_read_b128 v[168:171], v200 offset:17408
	ds_read_b128 v[172:175], v200 offset:18432
	ds_read_b128 v[176:179], v200 offset:19456
	s_add_i32 m0, s28, 0xc000
	ds_read_b128 v[180:183], v141
	ds_read_b128 v[184:187], v141 offset:1024
	ds_read_b128 v[188:191], v141 offset:2048
	ds_read_b128 v[192:195], v141 offset:3072
	ds_read_b128 v[196:199], v141 offset:4096
	ds_read_b128 v[222:225], v141 offset:5120
	ds_read_b128 v[226:229], v141 offset:6144
	global_load_lds_dwordx4 v134, s[72:73]
	s_add_i32 m0, s28, 0xe000
	ds_read_b128 v[230:233], v141 offset:7168
	global_load_lds_dwordx4 v136, s[72:73]
	s_add_u32 s4, s72, 0x100
	s_addc_u32 s5, s73, 0
	s_cmpk_eq_i32 s83, 0x54
	s_cselect_b32 s57, s45, s5
	s_cselect_b32 s56, s44, s4
	s_cselect_b32 s53, s55, s82
	s_cselect_b32 s52, s54, s81

; #define PG8_STAGE(bufoff, gbase, voff) do { _Pragma("unroll") for (int _i = 0; _i < 2; ++_i) \
;         __builtin_amdgcn_global_load_lds((const unsigned*)((const char*)(gbase) + (voff)[_i]), (PG8_LAS unsigned*)(lds + (bufoff) + ldsw + _i * 8192), 16, 0, 0); } while (0)
; #define PG8_LDA(dst, b, h) do { _Pragma("unroll") for (int m = 0; m < 4; ++m) _Pragma("unroll") for (int k = 0; k < 2; ++k) dst[m][k] = *(const PG8_LAS bf16x8*)(lds + PG8_SA(b, h) + aoff + m * 2048 + k * 1024); } while (0)
; #define PG8_LDB(dst, b, h) do { _Pragma("unroll") for (int n = 0; n < 2; ++n) _Pragma("unroll") for (int k = 0; k < 2; ++k) dst[n][k] = *(const PG8_LAS bf16x8*)(lds + PG8_SB(b, h) + boff + n * 2048 + k * 1024); } while (0)
; #define PG8_MMA(ai, bj, At, Bt) do { __builtin_amdgcn_s_setprio(1); _Pragma("unroll") for (int m = 0; m < 4; ++m) _Pragma("unroll") for (int n = 0; n < 2; ++n) _Pragma("unroll") for (int k = 0; k < 2; ++k) \
;         acc[ai][bj][m][n] = __builtin_amdgcn_mfma_f32_16x16x32_bf16(Bt[n][k], At[m][k], acc[ai][bj][m][n], 0, 0, 0); __builtin_amdgcn_s_setprio(0); } while (0)
; #define PG8_WAIT_V(n) asm volatile("s_waitcnt vmcnt(" #n ")" ::: "memory")
; #define PG8_WAIT_L(n) asm volatile("s_waitcnt lgkmcnt(" #n ")" ::: "memory")
; #define PG8_BAR __builtin_amdgcn_s_barrier()
; #define PG8_SCHED __builtin_amdgcn_sched_barrier(0)
; template <class Epi, class Sched, bool ALIGN_EPI = false, bool SP2 = false>
; __device__ __forceinline__ void gemm_phase(PG8_LAS unsigned char* lds, const Gemm g, const Sched& S, const Epi& E) {
;     ...
;             PG8_LDB(B0, 0, 0); PG8_LDB(B1, 0, 1); PG8_SCHED; PG8_LDA(At, 0, 0); PG8_STAGE(PG8_SA(1, 1), a1 + hstep, voffA);
;             PG8_WAIT_V(8); PG8_WAIT_L(0); PG8_BAR; PG8_MMA(0, 0, At, B0); PG8_MMA(0, 1, At, B1); PG8_BAR; PG8_SCHED;
;             PG8_LDA(At, 0, 1); PG8_STAGE(PG8_SB(0, 0), b2, voffB); PG8_STAGE(PG8_SB(0, 1), b2 + hstep, voffB); PG8_STAGE(PG8_SA(0, 0), a2, voffA);
	s_waitcnt vmcnt(8)
	s_waitcnt lgkmcnt(0)
	s_barrier
	v_mfma_f32_16x16x32_bf16 v[124:127], v[142:145], v[180:183], v[124:127]
	v_mfma_f32_16x16x32_bf16 v[120:123], v[150:153], v[180:183], v[120:123]
	v_mfma_f32_16x16x32_bf16 v[116:119], v[142:145], v[188:191], v[116:119]
	v_mfma_f32_16x16x32_bf16 v[112:115], v[150:153], v[188:191], v[112:115]
	v_mfma_f32_16x16x32_bf16 v[100:103], v[142:145], v[196:199], v[100:103]
	v_mfma_f32_16x16x32_bf16 v[96:99], v[150:153], v[196:199], v[96:99]
	v_mfma_f32_16x16x32_bf16 v[84:87], v[142:145], v[226:229], v[84:87]
	v_mfma_f32_16x16x32_bf16 v[80:83], v[150:153], v[226:229], v[80:83]
	v_mfma_f32_16x16x32_bf16 v[124:127], v[146:149], v[184:187], v[124:127]
	v_mfma_f32_16x16x32_bf16 v[120:123], v[154:157], v[184:187], v[120:123]
	v_mfma_f32_16x16x32_bf16 v[116:119], v[146:149], v[192:195], v[116:119]
	v_mfma_f32_16x16x32_bf16 v[112:115], v[154:157], v[192:195], v[112:115]
	v_mfma_f32_16x16x32_bf16 v[100:103], v[146:149], v[222:225], v[100:103]
	v_mfma_f32_16x16x32_bf16 v[96:99], v[154:157], v[222:225], v[96:99]
	v_mfma_f32_16x16x32_bf16 v[84:87], v[146:149], v[230:233], v[84:87]
	v_mfma_f32_16x16x32_bf16 v[80:83], v[154:157], v[230:233], v[80:83]
	v_mfma_f32_16x16x32_bf16 v[108:111], v[164:167], v[180:183], v[108:111]
	v_mfma_f32_16x16x32_bf16 v[104:107], v[172:175], v[180:183], v[104:107]
	v_mfma_f32_16x16x32_bf16 v[92:95], v[164:167], v[188:191], v[92:95]
	v_mfma_f32_16x16x32_bf16 v[88:91], v[172:175], v[188:191], v[88:91]
	v_mfma_f32_16x16x32_bf16 v[76:79], v[164:167], v[196:199], v[76:79]
	v_mfma_f32_16x16x32_bf16 v[72:75], v[172:175], v[196:199], v[72:75]
	v_mfma_f32_16x16x32_bf16 v[68:71], v[164:167], v[226:229], v[68:71]
	v_mfma_f32_16x16x32_bf16 v[64:67], v[172:175], v[226:229], v[64:67]
	v_mfma_f32_16x16x32_bf16 v[108:111], v[168:171], v[184:187], v[108:111]
	v_mfma_f32_16x16x32_bf16 v[104:107], v[176:179], v[184:187], v[104:107]
	v_mfma_f32_16x16x32_bf16 v[92:95], v[168:171], v[192:195], v[92:95]
	v_mfma_f32_16x16x32_bf16 v[88:91], v[176:179], v[192:195], v[88:91]
	v_mfma_f32_16x16x32_bf16 v[76:79], v[168:171], v[222:225], v[76:79]
	v_mfma_f32_16x16x32_bf16 v[72:75], v[176:179], v[222:225], v[72:75]
	v_mfma_f32_16x16x32_bf16 v[68:71], v[168:171], v[230:233], v[68:71]
	v_mfma_f32_16x16x32_bf16 v[64:67], v[176:179], v[230:233], v[64:67]
	s_barrier
	s_add_i32 s72, s84, s24
	s_mov_b32 m0, s72
	ds_read_b128 v[180:183], v141 offset:16384
	ds_read_b128 v[184:187], v141 offset:17408
	ds_read_b128 v[188:191], v141 offset:18432
	ds_read_b128 v[192:195], v141 offset:19456
	global_load_lds_dwordx4 v160, s[52:53]
	s_add_i32 m0, s72, 0x2000
	s_add_u32 s72, s52, 0x160000
	s_addc_u32 s73, s53, 0
	s_add_i32 s84, s85, s24
	global_load_lds_dwordx4 v128, s[52:53]
	s_mov_b32 m0, s84
	ds_read_b128 v[196:199], v141 offset:20480
	global_load_lds_dwordx4 v160, s[72:73]
	s_add_i32 m0, s84, 0x2000
	ds_read_b128 v[222:225], v141 offset:21504
	global_load_lds_dwordx4 v128, s[72:73]
	s_mov_b32 m0, s28
	ds_read_b128 v[226:229], v141 offset:22528
	global_load_lds_dwordx4 v132, s[56:57]
	s_mov_b32 m0, s29
	ds_read_b128 v[230:233], v141 offset:23552
	global_load_lds_dwordx4 v130, s[56:57]
	s_add_u32 s98, s56, 0x80
	s_addc_u32 s99, s57, 0


; #define PG8_STAGE(bufoff, gbase, voff) do { _Pragma("unroll") for (int _i = 0; _i < 2; ++_i) \
;         __builtin_amdgcn_global_load_lds((const unsigned*)((const char*)(gbase) + (voff)[_i]), (PG8_LAS unsigned*)(lds + (bufoff) + ldsw + _i * 8192), 16, 0, 0); } while (0)
; #define PG8_LDA(dst, b, h) do { _Pragma("unroll") for (int m = 0; m < 4; ++m) _Pragma("unroll") for (int k = 0; k < 2; ++k) dst[m][k] = *(const PG8_LAS bf16x8*)(lds + PG8_SA(b, h) + aoff + m * 2048 + k * 1024); } while (0)
; #define PG8_LDB(dst, b, h) do { _Pragma("unroll") for (int n = 0; n < 2; ++n) _Pragma("unroll") for (int k = 0; k < 2; ++k) dst[n][k] = *(const PG8_LAS bf16x8*)(lds + PG8_SB(b, h) + boff + n * 2048 + k * 1024); } while (0)
; #define PG8_MMA(ai, bj, At, Bt) do { __builtin_amdgcn_s_setprio(1); _Pragma("unroll") for (int m = 0; m < 4; ++m) _Pragma("unroll") for (int n = 0; n < 2; ++n) _Pragma("unroll") for (int k = 0; k < 2; ++k) \
;         acc[ai][bj][m][n] = __builtin_amdgcn_mfma_f32_16x16x32_bf16(Bt[n][k], At[m][k], acc[ai][bj][m][n], 0, 0, 0); __builtin_amdgcn_s_setprio(0); } while (0)
; #define PG8_WAIT_V(n) asm volatile("s_waitcnt vmcnt(" #n ")" ::: "memory")
; #define PG8_WAIT_L(n) asm volatile("s_waitcnt lgkmcnt(" #n ")" ::: "memory")
; #define PG8_BAR __builtin_amdgcn_s_barrier()
; #define PG8_SCHED __builtin_amdgcn_sched_barrier(0)
; template <class Epi, class Sched, bool ALIGN_EPI = false, bool SP2 = false>
; __device__ __forceinline__ void gemm_phase(PG8_LAS unsigned char* lds, const Gemm g, const Sched& S, const Epi& E) {
;     ...
;             PG8_WAIT_V(8); PG8_WAIT_L(0); PG8_BAR; PG8_MMA(1, 0, At, B0); PG8_MMA(1, 1, At, B1); PG8_BAR; PG8_SCHED;
;             PG8_LDB(B0, 1, 0); PG8_LDB(B1, 1, 1); PG8_SCHED; PG8_LDA(At, 1, 0); PG8_STAGE(PG8_SA(0, 1), a2 + hstep, voffA);
	s_waitcnt vmcnt(8)
	s_waitcnt lgkmcnt(0)
	s_barrier
	v_mfma_f32_16x16x32_bf16 v[60:63], v[142:145], v[180:183], v[60:63]
	v_mfma_f32_16x16x32_bf16 v[56:59], v[150:153], v[180:183], v[56:59]
	v_mfma_f32_16x16x32_bf16 v[52:55], v[142:145], v[188:191], v[52:55]
	v_mfma_f32_16x16x32_bf16 v[48:51], v[150:153], v[188:191], v[48:51]
	v_mfma_f32_16x16x32_bf16 v[36:39], v[142:145], v[196:199], v[36:39]
	v_mfma_f32_16x16x32_bf16 v[32:35], v[150:153], v[196:199], v[32:35]
	v_mfma_f32_16x16x32_bf16 v[20:23], v[142:145], v[226:229], v[20:23]
	v_mfma_f32_16x16x32_bf16 v[16:19], v[150:153], v[226:229], v[16:19]
	v_mfma_f32_16x16x32_bf16 v[60:63], v[146:149], v[184:187], v[60:63]
	v_mfma_f32_16x16x32_bf16 v[56:59], v[154:157], v[184:187], v[56:59]
	v_mfma_f32_16x16x32_bf16 v[52:55], v[146:149], v[192:195], v[52:55]
	v_mfma_f32_16x16x32_bf16 v[48:51], v[154:157], v[192:195], v[48:51]
	v_mfma_f32_16x16x32_bf16 v[36:39], v[146:149], v[222:225], v[36:39]
	v_mfma_f32_16x16x32_bf16 v[32:35], v[154:157], v[222:225], v[32:35]
	v_mfma_f32_16x16x32_bf16 v[20:23], v[146:149], v[230:233], v[20:23]
	v_mfma_f32_16x16x32_bf16 v[16:19], v[154:157], v[230:233], v[16:19]
	v_mfma_f32_16x16x32_bf16 v[44:47], v[164:167], v[180:183], v[44:47]
	v_mfma_f32_16x16x32_bf16 v[40:43], v[172:175], v[180:183], v[40:43]
	v_mfma_f32_16x16x32_bf16 v[28:31], v[164:167], v[188:191], v[28:31]
	v_mfma_f32_16x16x32_bf16 v[24:27], v[172:175], v[188:191], v[24:27]
	v_mfma_f32_16x16x32_bf16 v[12:15], v[164:167], v[196:199], v[12:15]
	v_mfma_f32_16x16x32_bf16 v[8:11], v[172:175], v[196:199], v[8:11]
	v_mfma_f32_16x16x32_bf16 v[4:7], v[164:167], v[226:229], v[4:7]
	v_mfma_f32_16x16x32_bf16 v[0:3], v[172:175], v[226:229], v[0:3]
	v_mfma_f32_16x16x32_bf16 v[44:47], v[168:171], v[184:187], v[44:47]
	v_mfma_f32_16x16x32_bf16 v[40:43], v[176:179], v[184:187], v[40:43]
	v_mfma_f32_16x16x32_bf16 v[28:31], v[168:171], v[192:195], v[28:31]
	v_mfma_f32_16x16x32_bf16 v[24:27], v[176:179], v[192:195], v[24:27]
	v_mfma_f32_16x16x32_bf16 v[12:15], v[168:171], v[222:225], v[12:15]
	v_mfma_f32_16x16x32_bf16 v[8:11], v[176:179], v[222:225], v[8:11]
	v_mfma_f32_16x16x32_bf16 v[4:7], v[168:171], v[230:233], v[4:7]
	v_mfma_f32_16x16x32_bf16 v[0:3], v[176:179], v[230:233], v[0:3]
	s_barrier
	s_add_i32 s72, 0, 0x18000
	s_add_i32 s73, 0, 0x1c000
	ds_read_b128 v[142:145], v200 offset:32768
	ds_read_b128 v[146:149], v200 offset:33792
	ds_read_b128 v[150:153], v200 offset:34816
	ds_read_b128 v[154:157], v200 offset:35840
	ds_read_b128 v[164:167], v200 offset:49152
	ds_read_b128 v[168:171], v200 offset:50176
	ds_read_b128 v[172:175], v200 offset:51200
	ds_read_b128 v[176:179], v200 offset:52224
	s_add_u32 s56, s56, 0x160000
	s_addc_u32 s57, s57, 0
	s_mov_b32 m0, s59
	ds_read_b128 v[180:183], v141 offset:32768
	ds_read_b128 v[184:187], v141 offset:33792
	ds_read_b128 v[188:191], v141 offset:34816
	ds_read_b128 v[192:195], v141 offset:35840
	ds_read_b128 v[196:199], v141 offset:36864
	ds_read_b128 v[222:225], v141 offset:37888
	ds_read_b128 v[226:229], v141 offset:38912
	global_load_lds_dwordx4 v132, s[56:57]
	s_mov_b32 m0, s63
	ds_read_b128 v[230:233], v141 offset:39936
	global_load_lds_dwordx4 v130, s[56:57]

; #define PG8_STAGE(bufoff, gbase, voff) do { _Pragma("unroll") for (int _i = 0; _i < 2; ++_i) \
;         __builtin_amdgcn_global_load_lds((const unsigned*)((const char*)(gbase) + (voff)[_i]), (PG8_LAS unsigned*)(lds + (bufoff) + ldsw + _i * 8192), 16, 0, 0); } while (0)
; #define PG8_LDA(dst, b, h) do { _Pragma("unroll") for (int m = 0; m < 4; ++m) _Pragma("unroll") for (int k = 0; k < 2; ++k) dst[m][k] = *(const PG8_LAS bf16x8*)(lds + PG8_SA(b, h) + aoff + m * 2048 + k * 1024); } while (0)
; #define PG8_MMA(ai, bj, At, Bt) do { __builtin_amdgcn_s_setprio(1); _Pragma("unroll") for (int m = 0; m < 4; ++m) _Pragma("unroll") for (int n = 0; n < 2; ++n) _Pragma("unroll") for (int k = 0; k < 2; ++k) \
;         acc[ai][bj][m][n] = __builtin_amdgcn_mfma_f32_16x16x32_bf16(Bt[n][k], At[m][k], acc[ai][bj][m][n], 0, 0, 0); __builtin_amdgcn_s_setprio(0); } while (0)
; #define PG8_WAIT_V(n) asm volatile("s_waitcnt vmcnt(" #n ")" ::: "memory")
; #define PG8_WAIT_L(n) asm volatile("s_waitcnt lgkmcnt(" #n ")" ::: "memory")
; #define PG8_BAR __builtin_amdgcn_s_barrier()
; #define PG8_SCHED __builtin_amdgcn_sched_barrier(0)
; template <class Epi, class Sched, bool ALIGN_EPI = false, bool SP2 = false>
; __device__ __forceinline__ void gemm_phase(PG8_LAS unsigned char* lds, const Gemm g, const Sched& S, const Epi& E) {
;     ...
;             PG8_WAIT_V(8); PG8_WAIT_L(0); PG8_BAR; PG8_MMA(0, 0, At, B0); PG8_MMA(0, 1, At, B1); PG8_BAR; PG8_SCHED;
;             PG8_LDA(At, 1, 1); PG8_STAGE(PG8_SB(1, 0), b3, voffB); PG8_STAGE(PG8_SB(1, 1), b3 + hstep, voffB); PG8_STAGE(PG8_SA(1, 0), a3, voffA);
	s_waitcnt vmcnt(8)
	s_waitcnt lgkmcnt(0)
	s_barrier
	v_mfma_f32_16x16x32_bf16 v[124:127], v[142:145], v[180:183], v[124:127]
	v_mfma_f32_16x16x32_bf16 v[120:123], v[150:153], v[180:183], v[120:123]
	v_mfma_f32_16x16x32_bf16 v[116:119], v[142:145], v[188:191], v[116:119]
	v_mfma_f32_16x16x32_bf16 v[112:115], v[150:153], v[188:191], v[112:115]
	v_mfma_f32_16x16x32_bf16 v[100:103], v[142:145], v[196:199], v[100:103]
	v_mfma_f32_16x16x32_bf16 v[96:99], v[150:153], v[196:199], v[96:99]
	v_mfma_f32_16x16x32_bf16 v[84:87], v[142:145], v[226:229], v[84:87]
	v_mfma_f32_16x16x32_bf16 v[80:83], v[150:153], v[226:229], v[80:83]
	v_mfma_f32_16x16x32_bf16 v[124:127], v[146:149], v[184:187], v[124:127]
	v_mfma_f32_16x16x32_bf16 v[120:123], v[154:157], v[184:187], v[120:123]
	v_mfma_f32_16x16x32_bf16 v[116:119], v[146:149], v[192:195], v[116:119]
	v_mfma_f32_16x16x32_bf16 v[112:115], v[154:157], v[192:195], v[112:115]
	v_mfma_f32_16x16x32_bf16 v[100:103], v[146:149], v[222:225], v[100:103]
	v_mfma_f32_16x16x32_bf16 v[96:99], v[154:157], v[222:225], v[96:99]
	v_mfma_f32_16x16x32_bf16 v[84:87], v[146:149], v[230:233], v[84:87]
	v_mfma_f32_16x16x32_bf16 v[80:83], v[154:157], v[230:233], v[80:83]
	v_mfma_f32_16x16x32_bf16 v[108:111], v[164:167], v[180:183], v[108:111]
	v_mfma_f32_16x16x32_bf16 v[104:107], v[172:175], v[180:183], v[104:107]
	v_mfma_f32_16x16x32_bf16 v[92:95], v[164:167], v[188:191], v[92:95]
	v_mfma_f32_16x16x32_bf16 v[88:91], v[172:175], v[188:191], v[88:91]
	v_mfma_f32_16x16x32_bf16 v[76:79], v[164:167], v[196:199], v[76:79]
	v_mfma_f32_16x16x32_bf16 v[72:75], v[172:175], v[196:199], v[72:75]
	v_mfma_f32_16x16x32_bf16 v[68:71], v[164:167], v[226:229], v[68:71]
	v_mfma_f32_16x16x32_bf16 v[64:67], v[172:175], v[226:229], v[64:67]
	v_mfma_f32_16x16x32_bf16 v[108:111], v[168:171], v[184:187], v[108:111]
	v_mfma_f32_16x16x32_bf16 v[104:107], v[176:179], v[184:187], v[104:107]
	v_mfma_f32_16x16x32_bf16 v[92:95], v[168:171], v[192:195], v[92:95]
	v_mfma_f32_16x16x32_bf16 v[88:91], v[176:179], v[192:195], v[88:91]
	v_mfma_f32_16x16x32_bf16 v[76:79], v[168:171], v[222:225], v[76:79]
	v_mfma_f32_16x16x32_bf16 v[72:75], v[176:179], v[222:225], v[72:75]
	v_mfma_f32_16x16x32_bf16 v[68:71], v[168:171], v[230:233], v[68:71]
	v_mfma_f32_16x16x32_bf16 v[64:67], v[176:179], v[230:233], v[64:67]
	s_barrier
	s_add_i32 s56, s72, s24
	s_mov_b32 m0, s56
	ds_read_b128 v[180:183], v141 offset:49152
	ds_read_b128 v[184:187], v141 offset:50176
	ds_read_b128 v[188:191], v141 offset:51200
	ds_read_b128 v[192:195], v141 offset:52224
	s_add_u32 s52, s52, 0x80
	s_addc_u32 s53, s53, 0
	global_load_lds_dwordx4 v160, s[52:53]
	s_add_i32 m0, s56, 0x2000
	s_add_i32 s56, s73, s24
	global_load_lds_dwordx4 v128, s[52:53]
	s_add_u32 s52, s52, 0x160000
	s_addc_u32 s53, s53, 0
	s_mov_b32 m0, s56
	ds_read_b128 v[196:199], v141 offset:53248
	global_load_lds_dwordx4 v160, s[52:53]
	s_add_i32 m0, s56, 0x2000
	ds_read_b128 v[222:225], v141 offset:54272
	global_load_lds_dwordx4 v128, s[52:53]
	s_mov_b32 m0, s74
	ds_read_b128 v[226:229], v141 offset:55296
	global_load_lds_dwordx4 v132, s[98:99]
	s_mov_b32 m0, s75
	ds_read_b128 v[230:233], v141 offset:56320
	global_load_lds_dwordx4 v130, s[98:99]


; #define PG8_STAGE(bufoff, gbase, voff) do { _Pragma("unroll") for (int _i = 0; _i < 2; ++_i) \
;         __builtin_amdgcn_global_load_lds((const unsigned*)((const char*)(gbase) + (voff)[_i]), (PG8_LAS unsigned*)(lds + (bufoff) + ldsw + _i * 8192), 16, 0, 0); } while (0)
; #define PG8_LDA(dst, b, h) do { _Pragma("unroll") for (int m = 0; m < 4; ++m) _Pragma("unroll") for (int k = 0; k < 2; ++k) dst[m][k] = *(const PG8_LAS bf16x8*)(lds + PG8_SA(b, h) + aoff + m * 2048 + k * 1024); } while (0)
; #define PG8_LDB(dst, b, h) do { _Pragma("unroll") for (int n = 0; n < 2; ++n) _Pragma("unroll") for (int k = 0; k < 2; ++k) dst[n][k] = *(const PG8_LAS bf16x8*)(lds + PG8_SB(b, h) + boff + n * 2048 + k * 1024); } while (0)
; template <class Epi, class Sched, bool ALIGN_EPI = false, bool SP2 = false>
; __device__ __forceinline__ void gemm_phase(PG8_LAS unsigned char* lds, const Gemm g, const Sched& S, const Epi& E) {
;     ...
;             PG8_WAIT_V(8); PG8_WAIT_L(0); PG8_BAR; PG8_MMA(1, 0, At, B0); PG8_MMA(1, 1, At, B1); PG8_BAR; PG8_SCHED;
;             } else {
;             PG8_LDB(B0, 0, 0); PG8_SCHED; PG8_LDA(At, 0, 0); PG8_STAGE(PG8_SA(1, 1), a1 + hstep, voffA);
;             PG8_WAIT_L(8); PG8_BAR; PG8_WAIT_L(0); PG8_MMA(0, 0, At, B0); PG8_BAR; PG8_SCHED;
;             PG8_LDB(B1, 0, 1); PG8_STAGE(PG8_SB(0, 0), b2, voffB);
;             PG8_BAR; PG8_WAIT_L(0); PG8_MMA(0, 1, At, B1); PG8_BAR;
;             PG8_LDA(At, 0, 1); PG8_STAGE(PG8_SA(0, 0), a2, voffA);
;             PG8_BAR; PG8_WAIT_L(0); PG8_MMA(1, 0, At, B0); PG8_BAR; PG8_SCHED;
;             PG8_STAGE(PG8_SB(0, 1), b2 + hstep, voffB);
;             PG8_WAIT_V(6); PG8_BAR; PG8_MMA(1, 1, At, B1); PG8_BAR;
;             PG8_LDB(B0, 1, 0); PG8_SCHED; PG8_LDA(At, 1, 0); PG8_STAGE(PG8_SA(0, 1), a2 + hstep, voffA);
;             PG8_WAIT_L(8); PG8_BAR; PG8_WAIT_L(0); PG8_MMA(0, 0, At, B0); PG8_BAR; PG8_SCHED;
;             PG8_LDB(B1, 1, 1); PG8_STAGE(PG8_SB(1, 0), b3, voffB);
;             PG8_BAR; PG8_WAIT_L(0); PG8_MMA(0, 1, At, B1); PG8_BAR;
;             PG8_LDA(At, 1, 1); PG8_STAGE(PG8_SA(1, 0), a3, voffA);
;             PG8_BAR; PG8_WAIT_L(0); PG8_MMA(1, 0, At, B0); PG8_BAR; PG8_SCHED;
;             PG8_STAGE(PG8_SB(1, 1), b3 + hstep, voffB);
;             PG8_WAIT_V(6); PG8_BAR; PG8_MMA(1, 1, At, B1); PG8_BAR;
;             }
;         }
;         if constexpr (ALIGN_EPI) { if (wr == 0) PG8_BAR; }
	s_add_i32 s83, s83, 2
	s_add_u32 s81, s81, 0x100
	s_addc_u32 s82, s82, 0
	s_waitcnt vmcnt(8)
	s_waitcnt lgkmcnt(0)
	s_barrier
	v_mfma_f32_16x16x32_bf16 v[60:63], v[142:145], v[180:183], v[60:63]
	v_mfma_f32_16x16x32_bf16 v[56:59], v[150:153], v[180:183], v[56:59]
	v_mfma_f32_16x16x32_bf16 v[52:55], v[142:145], v[188:191], v[52:55]
	v_mfma_f32_16x16x32_bf16 v[48:51], v[150:153], v[188:191], v[48:51]
	v_mfma_f32_16x16x32_bf16 v[36:39], v[142:145], v[196:199], v[36:39]
	v_mfma_f32_16x16x32_bf16 v[32:35], v[150:153], v[196:199], v[32:35]
	v_mfma_f32_16x16x32_bf16 v[20:23], v[142:145], v[226:229], v[20:23]
	v_mfma_f32_16x16x32_bf16 v[16:19], v[150:153], v[226:229], v[16:19]
	v_mfma_f32_16x16x32_bf16 v[60:63], v[146:149], v[184:187], v[60:63]
	v_mfma_f32_16x16x32_bf16 v[56:59], v[154:157], v[184:187], v[56:59]
	v_mfma_f32_16x16x32_bf16 v[52:55], v[146:149], v[192:195], v[52:55]
	v_mfma_f32_16x16x32_bf16 v[48:51], v[154:157], v[192:195], v[48:51]
	v_mfma_f32_16x16x32_bf16 v[36:39], v[146:149], v[222:225], v[36:39]
	v_mfma_f32_16x16x32_bf16 v[32:35], v[154:157], v[222:225], v[32:35]
	v_mfma_f32_16x16x32_bf16 v[20:23], v[146:149], v[230:233], v[20:23]
	v_mfma_f32_16x16x32_bf16 v[16:19], v[154:157], v[230:233], v[16:19]
	v_mfma_f32_16x16x32_bf16 v[44:47], v[164:167], v[180:183], v[44:47]
	v_mfma_f32_16x16x32_bf16 v[40:43], v[172:175], v[180:183], v[40:43]
	v_mfma_f32_16x16x32_bf16 v[28:31], v[164:167], v[188:191], v[28:31]
	v_mfma_f32_16x16x32_bf16 v[24:27], v[172:175], v[188:191], v[24:27]
	v_mfma_f32_16x16x32_bf16 v[12:15], v[164:167], v[196:199], v[12:15]
	v_mfma_f32_16x16x32_bf16 v[8:11], v[172:175], v[196:199], v[8:11]
	v_mfma_f32_16x16x32_bf16 v[4:7], v[164:167], v[226:229], v[4:7]
	v_mfma_f32_16x16x32_bf16 v[0:3], v[172:175], v[226:229], v[0:3]
	v_mfma_f32_16x16x32_bf16 v[44:47], v[168:171], v[184:187], v[44:47]
	v_mfma_f32_16x16x32_bf16 v[40:43], v[176:179], v[184:187], v[40:43]
	v_mfma_f32_16x16x32_bf16 v[28:31], v[168:171], v[192:195], v[28:31]
	v_mfma_f32_16x16x32_bf16 v[24:27], v[176:179], v[192:195], v[24:27]
	v_mfma_f32_16x16x32_bf16 v[12:15], v[168:171], v[222:225], v[12:15]
	v_mfma_f32_16x16x32_bf16 v[8:11], v[176:179], v[222:225], v[8:11]
	v_mfma_f32_16x16x32_bf16 v[4:7], v[168:171], v[230:233], v[4:7]
	v_mfma_f32_16x16x32_bf16 v[0:3], v[176:179], v[230:233], v[0:3]
	s_barrier
	s_cmpk_gt_u32 s83, 0x55
	s_mov_b64 s[72:73], s[4:5]
	s_cbranch_scc0 .LBB0_52
	s_and_b64 vcc, exec, s[42:43]
	s_cbranch_vccz .LBB0_55
	s_barrier

; #define PG8_STAGE(bufoff, gbase, voff) do { _Pragma("unroll") for (int _i = 0; _i < 2; ++_i) \
;         __builtin_amdgcn_global_load_lds((const unsigned*)((const char*)(gbase) + (voff)[_i]), (PG8_LAS unsigned*)(lds + (bufoff) + ldsw + _i * 8192), 16, 0, 0); } while (0)
; #define PG8_LDA(dst, b, h) do { _Pragma("unroll") for (int m = 0; m < 4; ++m) _Pragma("unroll") for (int k = 0; k < 2; ++k) dst[m][k] = *(const PG8_LAS bf16x8*)(lds + PG8_SA(b, h) + aoff + m * 2048 + k * 1024); } while (0)
; #define PG8_LDB(dst, b, h) do { _Pragma("unroll") for (int n = 0; n < 2; ++n) _Pragma("unroll") for (int k = 0; k < 2; ++k) dst[n][k] = *(const PG8_LAS bf16x8*)(lds + PG8_SB(b, h) + boff + n * 2048 + k * 1024); } while (0)
; #define PG8_SCHED __builtin_amdgcn_sched_barrier(0)
; template <class Epi, class Sched, bool ALIGN_EPI = false, bool SP2 = false>
; __device__ __forceinline__ void gemm_phase(PG8_LAS unsigned char* lds, const Gemm g, const Sched& S, const Epi& E) {
;     ...
;             const bool last = (t == nt - 2);
;             const char* a1 = cA + (size_t)(t + 1) * kstep;
;             const char* a2 = last ? nA : cA + (size_t)(t + 2) * kstep; const char* b2 = last ? nB : cB + (size_t)(t + 2) * kstep;
;             const char* a3 = a2 + kstep; const char* b3 = b2 + kstep;
;             if (last && has_next) S.a_ready(nxt);
;             if constexpr (SP2) {
;             PG8_LDB(B0, 0, 0); PG8_LDB(B1, 0, 1); PG8_SCHED; PG8_LDA(At, 0, 0); PG8_STAGE(PG8_SA(1, 1), a1 + hstep, voffA);
.LBB0_86:
	s_add_i32 s88, 0, 0x10000
	s_add_i32 s90, 0, 0x14000
	ds_read_b128 v[140:143], v200
	ds_read_b128 v[150:153], v200 offset:1024
	ds_read_b128 v[154:157], v200 offset:2048
	ds_read_b128 v[164:167], v200 offset:3072
	ds_read_b128 v[168:171], v200 offset:16384
	ds_read_b128 v[172:175], v200 offset:17408
	ds_read_b128 v[176:179], v200 offset:18432
	ds_read_b128 v[180:183], v200 offset:19456
	s_add_i32 m0, s63, 0xc000
	ds_read_b128 v[184:187], v149
	ds_read_b128 v[188:191], v149 offset:1024
	ds_read_b128 v[192:195], v149 offset:2048
	ds_read_b128 v[196:199], v149 offset:3072
	ds_read_b128 v[222:225], v149 offset:4096
	ds_read_b128 v[226:229], v149 offset:5120
	ds_read_b128 v[230:233], v149 offset:6144
	global_load_lds_dwordx4 v136, s[82:83]
	s_add_i32 m0, s63, 0xe000
	ds_read_b128 v[234:237], v149 offset:7168
	global_load_lds_dwordx4 v138, s[82:83]
	s_add_u32 s4, s82, 0xfffc0080
	s_addc_u32 s5, s83, -1
	s_cmp_eq_u32 s87, 12
	s_cselect_b32 s53, s7, s5
	s_cselect_b32 s52, s15, s4
	s_cselect_b32 s5, s24, s43
	s_cselect_b32 s4, s28, s29

; #define PG8_STAGE(bufoff, gbase, voff) do { _Pragma("unroll") for (int _i = 0; _i < 2; ++_i) \
;         __builtin_amdgcn_global_load_lds((const unsigned*)((const char*)(gbase) + (voff)[_i]), (PG8_LAS unsigned*)(lds + (bufoff) + ldsw + _i * 8192), 16, 0, 0); } while (0)
; #define PG8_LDA(dst, b, h) do { _Pragma("unroll") for (int m = 0; m < 4; ++m) _Pragma("unroll") for (int k = 0; k < 2; ++k) dst[m][k] = *(const PG8_LAS bf16x8*)(lds + PG8_SA(b, h) + aoff + m * 2048 + k * 1024); } while (0)
; #define PG8_LDB(dst, b, h) do { _Pragma("unroll") for (int n = 0; n < 2; ++n) _Pragma("unroll") for (int k = 0; k < 2; ++k) dst[n][k] = *(const PG8_LAS bf16x8*)(lds + PG8_SB(b, h) + boff + n * 2048 + k * 1024); } while (0)
; #define PG8_MMA(ai, bj, At, Bt) do { __builtin_amdgcn_s_setprio(1); _Pragma("unroll") for (int m = 0; m < 4; ++m) _Pragma("unroll") for (int n = 0; n < 2; ++n) _Pragma("unroll") for (int k = 0; k < 2; ++k) \
;         acc[ai][bj][m][n] = __builtin_amdgcn_mfma_f32_16x16x32_bf16(Bt[n][k], At[m][k], acc[ai][bj][m][n], 0, 0, 0); __builtin_amdgcn_s_setprio(0); } while (0)
; #define PG8_WAIT_V(n) asm volatile("s_waitcnt vmcnt(" #n ")" ::: "memory")
; #define PG8_WAIT_L(n) asm volatile("s_waitcnt lgkmcnt(" #n ")" ::: "memory")
; #define PG8_BAR __builtin_amdgcn_s_barrier()
; #define PG8_SCHED __builtin_amdgcn_sched_barrier(0)
; template <class Epi, class Sched, bool ALIGN_EPI = false, bool SP2 = false>
; __device__ __forceinline__ void gemm_phase(PG8_LAS unsigned char* lds, const Gemm g, const Sched& S, const Epi& E) {
;     ...
;             PG8_LDB(B0, 0, 0); PG8_LDB(B1, 0, 1); PG8_SCHED; PG8_LDA(At, 0, 0); PG8_STAGE(PG8_SA(1, 1), a1 + hstep, voffA);
;             PG8_WAIT_V(8); PG8_WAIT_L(0); PG8_BAR; PG8_MMA(0, 0, At, B0); PG8_MMA(0, 1, At, B1); PG8_BAR; PG8_SCHED;
;             PG8_LDA(At, 0, 1); PG8_STAGE(PG8_SB(0, 0), b2, voffB); PG8_STAGE(PG8_SB(0, 1), b2 + hstep, voffB); PG8_STAGE(PG8_SA(0, 0), a2, voffA);
	s_waitcnt vmcnt(8)
	s_waitcnt lgkmcnt(0)
	s_barrier
	v_mfma_f32_16x16x32_bf16 v[124:127], v[140:143], v[184:187], v[124:127]
	v_mfma_f32_16x16x32_bf16 v[120:123], v[154:157], v[184:187], v[120:123]
	v_mfma_f32_16x16x32_bf16 v[108:111], v[140:143], v[192:195], v[108:111]
	v_mfma_f32_16x16x32_bf16 v[104:107], v[154:157], v[192:195], v[104:107]
	v_mfma_f32_16x16x32_bf16 v[92:95], v[140:143], v[222:225], v[92:95]
	v_mfma_f32_16x16x32_bf16 v[88:91], v[154:157], v[222:225], v[88:91]
	v_mfma_f32_16x16x32_bf16 v[76:79], v[140:143], v[230:233], v[76:79]
	v_mfma_f32_16x16x32_bf16 v[72:75], v[154:157], v[230:233], v[72:75]
	v_mfma_f32_16x16x32_bf16 v[124:127], v[150:153], v[188:191], v[124:127]
	v_mfma_f32_16x16x32_bf16 v[120:123], v[164:167], v[188:191], v[120:123]
	v_mfma_f32_16x16x32_bf16 v[108:111], v[150:153], v[196:199], v[108:111]
	v_mfma_f32_16x16x32_bf16 v[104:107], v[164:167], v[196:199], v[104:107]
	v_mfma_f32_16x16x32_bf16 v[92:95], v[150:153], v[226:229], v[92:95]
	v_mfma_f32_16x16x32_bf16 v[88:91], v[164:167], v[226:229], v[88:91]
	v_mfma_f32_16x16x32_bf16 v[76:79], v[150:153], v[234:237], v[76:79]
	v_mfma_f32_16x16x32_bf16 v[72:75], v[164:167], v[234:237], v[72:75]
	v_mfma_f32_16x16x32_bf16 v[116:119], v[168:171], v[184:187], v[116:119]
	v_mfma_f32_16x16x32_bf16 v[112:115], v[176:179], v[184:187], v[112:115]
	v_mfma_f32_16x16x32_bf16 v[100:103], v[168:171], v[192:195], v[100:103]
	v_mfma_f32_16x16x32_bf16 v[96:99], v[176:179], v[192:195], v[96:99]
	v_mfma_f32_16x16x32_bf16 v[84:87], v[168:171], v[222:225], v[84:87]
	v_mfma_f32_16x16x32_bf16 v[80:83], v[176:179], v[222:225], v[80:83]
	v_mfma_f32_16x16x32_bf16 v[68:71], v[168:171], v[230:233], v[68:71]
	v_mfma_f32_16x16x32_bf16 v[64:67], v[176:179], v[230:233], v[64:67]
	v_mfma_f32_16x16x32_bf16 v[116:119], v[172:175], v[188:191], v[116:119]
	v_mfma_f32_16x16x32_bf16 v[112:115], v[180:183], v[188:191], v[112:115]
	v_mfma_f32_16x16x32_bf16 v[100:103], v[172:175], v[196:199], v[100:103]
	v_mfma_f32_16x16x32_bf16 v[96:99], v[180:183], v[196:199], v[96:99]
	v_mfma_f32_16x16x32_bf16 v[84:87], v[172:175], v[226:229], v[84:87]
	v_mfma_f32_16x16x32_bf16 v[80:83], v[180:183], v[226:229], v[80:83]
	v_mfma_f32_16x16x32_bf16 v[68:71], v[172:175], v[234:237], v[68:71]
	v_mfma_f32_16x16x32_bf16 v[64:67], v[180:183], v[234:237], v[64:67]
	s_barrier
	s_add_i32 s88, s88, s59
	s_mov_b32 m0, s88
	ds_read_b128 v[184:187], v149 offset:16384
	ds_read_b128 v[188:191], v149 offset:17408
	ds_read_b128 v[192:195], v149 offset:18432
	ds_read_b128 v[196:199], v149 offset:19456
	global_load_lds_dwordx4 v130, s[4:5]
	s_add_i32 m0, s88, 0x2000
	s_add_u32 s88, s4, 0x40000
	s_addc_u32 s89, s5, 0
	s_add_i32 s90, s90, s59
	global_load_lds_dwordx4 v134, s[4:5]
	s_mov_b32 m0, s90
	ds_read_b128 v[222:225], v149 offset:20480
	global_load_lds_dwordx4 v130, s[88:89]
	s_add_i32 m0, s90, 0x2000
	ds_read_b128 v[226:229], v149 offset:21504
	global_load_lds_dwordx4 v134, s[88:89]
	s_mov_b32 m0, s63
	ds_read_b128 v[230:233], v149 offset:22528
	global_load_lds_dwordx4 v128, s[52:53]
	s_mov_b32 m0, s74
	ds_read_b128 v[234:237], v149 offset:23552
	global_load_lds_dwordx4 v132, s[52:53]
	s_add_u32 s98, s52, 0x80
	s_addc_u32 s99, s53, 0


; #define PG8_STAGE(bufoff, gbase, voff) do { _Pragma("unroll") for (int _i = 0; _i < 2; ++_i) \
;         __builtin_amdgcn_global_load_lds((const unsigned*)((const char*)(gbase) + (voff)[_i]), (PG8_LAS unsigned*)(lds + (bufoff) + ldsw + _i * 8192), 16, 0, 0); } while (0)
; #define PG8_LDA(dst, b, h) do { _Pragma("unroll") for (int m = 0; m < 4; ++m) _Pragma("unroll") for (int k = 0; k < 2; ++k) dst[m][k] = *(const PG8_LAS bf16x8*)(lds + PG8_SA(b, h) + aoff + m * 2048 + k * 1024); } while (0)
; #define PG8_LDB(dst, b, h) do { _Pragma("unroll") for (int n = 0; n < 2; ++n) _Pragma("unroll") for (int k = 0; k < 2; ++k) dst[n][k] = *(const PG8_LAS bf16x8*)(lds + PG8_SB(b, h) + boff + n * 2048 + k * 1024); } while (0)
; #define PG8_MMA(ai, bj, At, Bt) do { __builtin_amdgcn_s_setprio(1); _Pragma("unroll") for (int m = 0; m < 4; ++m) _Pragma("unroll") for (int n = 0; n < 2; ++n) _Pragma("unroll") for (int k = 0; k < 2; ++k) \
;         acc[ai][bj][m][n] = __builtin_amdgcn_mfma_f32_16x16x32_bf16(Bt[n][k], At[m][k], acc[ai][bj][m][n], 0, 0, 0); __builtin_amdgcn_s_setprio(0); } while (0)
; #define PG8_WAIT_V(n) asm volatile("s_waitcnt vmcnt(" #n ")" ::: "memory")
; #define PG8_WAIT_L(n) asm volatile("s_waitcnt lgkmcnt(" #n ")" ::: "memory")
; #define PG8_BAR __builtin_amdgcn_s_barrier()
; #define PG8_SCHED __builtin_amdgcn_sched_barrier(0)
; template <class Epi, class Sched, bool ALIGN_EPI = false, bool SP2 = false>
; __device__ __forceinline__ void gemm_phase(PG8_LAS unsigned char* lds, const Gemm g, const Sched& S, const Epi& E) {
;     ...
;             PG8_WAIT_V(8); PG8_WAIT_L(0); PG8_BAR; PG8_MMA(1, 0, At, B0); PG8_MMA(1, 1, At, B1); PG8_BAR; PG8_SCHED;
;             PG8_LDB(B0, 1, 0); PG8_LDB(B1, 1, 1); PG8_SCHED; PG8_LDA(At, 1, 0); PG8_STAGE(PG8_SA(0, 1), a2 + hstep, voffA);
	s_waitcnt vmcnt(8)
	s_waitcnt lgkmcnt(0)
	s_barrier
	v_mfma_f32_16x16x32_bf16 v[60:63], v[140:143], v[184:187], v[60:63]
	v_mfma_f32_16x16x32_bf16 v[56:59], v[154:157], v[184:187], v[56:59]
	v_mfma_f32_16x16x32_bf16 v[44:47], v[140:143], v[192:195], v[44:47]
	v_mfma_f32_16x16x32_bf16 v[40:43], v[154:157], v[192:195], v[40:43]
	v_mfma_f32_16x16x32_bf16 v[28:31], v[140:143], v[222:225], v[28:31]
	v_mfma_f32_16x16x32_bf16 v[24:27], v[154:157], v[222:225], v[24:27]
	v_mfma_f32_16x16x32_bf16 v[12:15], v[140:143], v[230:233], v[12:15]
	v_mfma_f32_16x16x32_bf16 v[8:11], v[154:157], v[230:233], v[8:11]
	v_mfma_f32_16x16x32_bf16 v[60:63], v[150:153], v[188:191], v[60:63]
	v_mfma_f32_16x16x32_bf16 v[56:59], v[164:167], v[188:191], v[56:59]
	v_mfma_f32_16x16x32_bf16 v[44:47], v[150:153], v[196:199], v[44:47]
	v_mfma_f32_16x16x32_bf16 v[40:43], v[164:167], v[196:199], v[40:43]
	v_mfma_f32_16x16x32_bf16 v[28:31], v[150:153], v[226:229], v[28:31]
	v_mfma_f32_16x16x32_bf16 v[24:27], v[164:167], v[226:229], v[24:27]
	v_mfma_f32_16x16x32_bf16 v[12:15], v[150:153], v[234:237], v[12:15]
	v_mfma_f32_16x16x32_bf16 v[8:11], v[164:167], v[234:237], v[8:11]
	v_mfma_f32_16x16x32_bf16 v[52:55], v[168:171], v[184:187], v[52:55]
	v_mfma_f32_16x16x32_bf16 v[48:51], v[176:179], v[184:187], v[48:51]
	v_mfma_f32_16x16x32_bf16 v[36:39], v[168:171], v[192:195], v[36:39]
	v_mfma_f32_16x16x32_bf16 v[32:35], v[176:179], v[192:195], v[32:35]
	v_mfma_f32_16x16x32_bf16 v[20:23], v[168:171], v[222:225], v[20:23]
	v_mfma_f32_16x16x32_bf16 v[16:19], v[176:179], v[222:225], v[16:19]
	v_mfma_f32_16x16x32_bf16 v[4:7], v[168:171], v[230:233], v[4:7]
	v_mfma_f32_16x16x32_bf16 v[0:3], v[176:179], v[230:233], v[0:3]
	v_mfma_f32_16x16x32_bf16 v[52:55], v[172:175], v[188:191], v[52:55]
	v_mfma_f32_16x16x32_bf16 v[48:51], v[180:183], v[188:191], v[48:51]
	v_mfma_f32_16x16x32_bf16 v[36:39], v[172:175], v[196:199], v[36:39]
	v_mfma_f32_16x16x32_bf16 v[32:35], v[180:183], v[196:199], v[32:35]
	v_mfma_f32_16x16x32_bf16 v[20:23], v[172:175], v[226:229], v[20:23]
	v_mfma_f32_16x16x32_bf16 v[16:19], v[180:183], v[226:229], v[16:19]
	v_mfma_f32_16x16x32_bf16 v[4:7], v[172:175], v[234:237], v[4:7]
	v_mfma_f32_16x16x32_bf16 v[0:3], v[180:183], v[234:237], v[0:3]
	s_barrier
	s_add_i32 s88, 0, 0x18000
	s_add_i32 s89, 0, 0x1c000
	ds_read_b128 v[140:143], v200 offset:32768
	ds_read_b128 v[150:153], v200 offset:33792
	ds_read_b128 v[154:157], v200 offset:34816
	ds_read_b128 v[164:167], v200 offset:35840
	ds_read_b128 v[168:171], v200 offset:49152
	ds_read_b128 v[172:175], v200 offset:50176
	ds_read_b128 v[176:179], v200 offset:51200
	ds_read_b128 v[180:183], v200 offset:52224
	s_add_u32 s52, s52, 0x40000
	s_addc_u32 s53, s53, 0
	s_mov_b32 m0, s75
	ds_read_b128 v[184:187], v149 offset:32768
	ds_read_b128 v[188:191], v149 offset:33792
	ds_read_b128 v[192:195], v149 offset:34816
	ds_read_b128 v[196:199], v149 offset:35840
	ds_read_b128 v[222:225], v149 offset:36864
	ds_read_b128 v[226:229], v149 offset:37888
	ds_read_b128 v[230:233], v149 offset:38912
	global_load_lds_dwordx4 v128, s[52:53]
	s_mov_b32 m0, s81
	ds_read_b128 v[234:237], v149 offset:39936
	global_load_lds_dwordx4 v132, s[52:53]

; #define PG8_STAGE(bufoff, gbase, voff) do { _Pragma("unroll") for (int _i = 0; _i < 2; ++_i) \
;         __builtin_amdgcn_global_load_lds((const unsigned*)((const char*)(gbase) + (voff)[_i]), (PG8_LAS unsigned*)(lds + (bufoff) + ldsw + _i * 8192), 16, 0, 0); } while (0)
; #define PG8_LDA(dst, b, h) do { _Pragma("unroll") for (int m = 0; m < 4; ++m) _Pragma("unroll") for (int k = 0; k < 2; ++k) dst[m][k] = *(const PG8_LAS bf16x8*)(lds + PG8_SA(b, h) + aoff + m * 2048 + k * 1024); } while (0)
; #define PG8_MMA(ai, bj, At, Bt) do { __builtin_amdgcn_s_setprio(1); _Pragma("unroll") for (int m = 0; m < 4; ++m) _Pragma("unroll") for (int n = 0; n < 2; ++n) _Pragma("unroll") for (int k = 0; k < 2; ++k) \
;         acc[ai][bj][m][n] = __builtin_amdgcn_mfma_f32_16x16x32_bf16(Bt[n][k], At[m][k], acc[ai][bj][m][n], 0, 0, 0); __builtin_amdgcn_s_setprio(0); } while (0)
; #define PG8_WAIT_V(n) asm volatile("s_waitcnt vmcnt(" #n ")" ::: "memory")
; #define PG8_WAIT_L(n) asm volatile("s_waitcnt lgkmcnt(" #n ")" ::: "memory")
; #define PG8_BAR __builtin_amdgcn_s_barrier()
; #define PG8_SCHED __builtin_amdgcn_sched_barrier(0)
; template <class Epi, class Sched, bool ALIGN_EPI = false, bool SP2 = false>
; __device__ __forceinline__ void gemm_phase(PG8_LAS unsigned char* lds, const Gemm g, const Sched& S, const Epi& E) {
;     ...
;             PG8_WAIT_V(8); PG8_WAIT_L(0); PG8_BAR; PG8_MMA(0, 0, At, B0); PG8_MMA(0, 1, At, B1); PG8_BAR; PG8_SCHED;
;             PG8_LDA(At, 1, 1); PG8_STAGE(PG8_SB(1, 0), b3, voffB); PG8_STAGE(PG8_SB(1, 1), b3 + hstep, voffB); PG8_STAGE(PG8_SA(1, 0), a3, voffA);
	s_waitcnt vmcnt(8)
	s_waitcnt lgkmcnt(0)
	s_barrier
	v_mfma_f32_16x16x32_bf16 v[124:127], v[140:143], v[184:187], v[124:127]
	v_mfma_f32_16x16x32_bf16 v[120:123], v[154:157], v[184:187], v[120:123]
	v_mfma_f32_16x16x32_bf16 v[108:111], v[140:143], v[192:195], v[108:111]
	v_mfma_f32_16x16x32_bf16 v[104:107], v[154:157], v[192:195], v[104:107]
	v_mfma_f32_16x16x32_bf16 v[92:95], v[140:143], v[222:225], v[92:95]
	v_mfma_f32_16x16x32_bf16 v[88:91], v[154:157], v[222:225], v[88:91]
	v_mfma_f32_16x16x32_bf16 v[76:79], v[140:143], v[230:233], v[76:79]
	v_mfma_f32_16x16x32_bf16 v[72:75], v[154:157], v[230:233], v[72:75]
	v_mfma_f32_16x16x32_bf16 v[124:127], v[150:153], v[188:191], v[124:127]
	v_mfma_f32_16x16x32_bf16 v[120:123], v[164:167], v[188:191], v[120:123]
	v_mfma_f32_16x16x32_bf16 v[108:111], v[150:153], v[196:199], v[108:111]
	v_mfma_f32_16x16x32_bf16 v[104:107], v[164:167], v[196:199], v[104:107]
	v_mfma_f32_16x16x32_bf16 v[92:95], v[150:153], v[226:229], v[92:95]
	v_mfma_f32_16x16x32_bf16 v[88:91], v[164:167], v[226:229], v[88:91]
	v_mfma_f32_16x16x32_bf16 v[76:79], v[150:153], v[234:237], v[76:79]
	v_mfma_f32_16x16x32_bf16 v[72:75], v[164:167], v[234:237], v[72:75]
	v_mfma_f32_16x16x32_bf16 v[116:119], v[168:171], v[184:187], v[116:119]
	v_mfma_f32_16x16x32_bf16 v[112:115], v[176:179], v[184:187], v[112:115]
	v_mfma_f32_16x16x32_bf16 v[100:103], v[168:171], v[192:195], v[100:103]
	v_mfma_f32_16x16x32_bf16 v[96:99], v[176:179], v[192:195], v[96:99]
	v_mfma_f32_16x16x32_bf16 v[84:87], v[168:171], v[222:225], v[84:87]
	v_mfma_f32_16x16x32_bf16 v[80:83], v[176:179], v[222:225], v[80:83]
	v_mfma_f32_16x16x32_bf16 v[68:71], v[168:171], v[230:233], v[68:71]
	v_mfma_f32_16x16x32_bf16 v[64:67], v[176:179], v[230:233], v[64:67]
	v_mfma_f32_16x16x32_bf16 v[116:119], v[172:175], v[188:191], v[116:119]
	v_mfma_f32_16x16x32_bf16 v[112:115], v[180:183], v[188:191], v[112:115]
	v_mfma_f32_16x16x32_bf16 v[100:103], v[172:175], v[196:199], v[100:103]
	v_mfma_f32_16x16x32_bf16 v[96:99], v[180:183], v[196:199], v[96:99]
	v_mfma_f32_16x16x32_bf16 v[84:87], v[172:175], v[226:229], v[84:87]
	v_mfma_f32_16x16x32_bf16 v[80:83], v[180:183], v[226:229], v[80:83]
	v_mfma_f32_16x16x32_bf16 v[68:71], v[172:175], v[234:237], v[68:71]
	v_mfma_f32_16x16x32_bf16 v[64:67], v[180:183], v[234:237], v[64:67]
	s_barrier
	s_add_i32 s52, s88, s59
	s_mov_b32 m0, s52
	ds_read_b128 v[184:187], v149 offset:49152
	ds_read_b128 v[188:191], v149 offset:50176
	ds_read_b128 v[192:195], v149 offset:51200
	ds_read_b128 v[196:199], v149 offset:52224
	s_add_u32 s4, s4, 0x80
	s_addc_u32 s5, s5, 0
	global_load_lds_dwordx4 v130, s[4:5]
	s_add_i32 m0, s52, 0x2000
	s_add_i32 s52, s89, s59
	global_load_lds_dwordx4 v134, s[4:5]
	s_add_u32 s4, s4, 0x40000
	s_addc_u32 s5, s5, 0
	s_mov_b32 m0, s52
	ds_read_b128 v[222:225], v149 offset:53248
	global_load_lds_dwordx4 v130, s[4:5]
	s_add_i32 m0, s52, 0x2000
	ds_read_b128 v[226:229], v149 offset:54272
	global_load_lds_dwordx4 v134, s[4:5]
	s_mov_b32 m0, s84
	ds_read_b128 v[230:233], v149 offset:55296
	global_load_lds_dwordx4 v128, s[98:99]
	s_mov_b32 m0, s85
	ds_read_b128 v[234:237], v149 offset:56320
	global_load_lds_dwordx4 v132, s[98:99]


; #define PG8_STAGE(bufoff, gbase, voff) do { _Pragma("unroll") for (int _i = 0; _i < 2; ++_i) \
;         __builtin_amdgcn_global_load_lds((const unsigned*)((const char*)(gbase) + (voff)[_i]), (PG8_LAS unsigned*)(lds + (bufoff) + ldsw + _i * 8192), 16, 0, 0); } while (0)
; #define PG8_LDA(dst, b, h) do { _Pragma("unroll") for (int m = 0; m < 4; ++m) _Pragma("unroll") for (int k = 0; k < 2; ++k) dst[m][k] = *(const PG8_LAS bf16x8*)(lds + PG8_SA(b, h) + aoff + m * 2048 + k * 1024); } while (0)
; #define PG8_LDB(dst, b, h) do { _Pragma("unroll") for (int n = 0; n < 2; ++n) _Pragma("unroll") for (int k = 0; k < 2; ++k) dst[n][k] = *(const PG8_LAS bf16x8*)(lds + PG8_SB(b, h) + boff + n * 2048 + k * 1024); } while (0)
; template <class Epi, class Sched, bool ALIGN_EPI = false, bool SP2 = false>
; __device__ __forceinline__ void gemm_phase(PG8_LAS unsigned char* lds, const Gemm g, const Sched& S, const Epi& E) {
;     ...
;             PG8_WAIT_V(8); PG8_WAIT_L(0); PG8_BAR; PG8_MMA(1, 0, At, B0); PG8_MMA(1, 1, At, B1); PG8_BAR; PG8_SCHED;
;             } else {
;             PG8_LDB(B0, 0, 0); PG8_SCHED; PG8_LDA(At, 0, 0); PG8_STAGE(PG8_SA(1, 1), a1 + hstep, voffA);
;             PG8_WAIT_L(8); PG8_BAR; PG8_WAIT_L(0); PG8_MMA(0, 0, At, B0); PG8_BAR; PG8_SCHED;
;             PG8_LDB(B1, 0, 1); PG8_STAGE(PG8_SB(0, 0), b2, voffB);
;             PG8_BAR; PG8_WAIT_L(0); PG8_MMA(0, 1, At, B1); PG8_BAR;
;             PG8_LDA(At, 0, 1); PG8_STAGE(PG8_SA(0, 0), a2, voffA);
;             PG8_BAR; PG8_WAIT_L(0); PG8_MMA(1, 0, At, B0); PG8_BAR; PG8_SCHED;
;             PG8_STAGE(PG8_SB(0, 1), b2 + hstep, voffB);
;             PG8_WAIT_V(6); PG8_BAR; PG8_MMA(1, 1, At, B1); PG8_BAR;
;             PG8_LDB(B0, 1, 0); PG8_SCHED; PG8_LDA(At, 1, 0); PG8_STAGE(PG8_SA(0, 1), a2 + hstep, voffA);
;             PG8_WAIT_L(8); PG8_BAR; PG8_WAIT_L(0); PG8_MMA(0, 0, At, B0); PG8_BAR; PG8_SCHED;
;             PG8_LDB(B1, 1, 1); PG8_STAGE(PG8_SB(1, 0), b3, voffB);
;             PG8_BAR; PG8_WAIT_L(0); PG8_MMA(0, 1, At, B1); PG8_BAR;
;             PG8_LDA(At, 1, 1); PG8_STAGE(PG8_SA(1, 0), a3, voffA);
;             PG8_BAR; PG8_WAIT_L(0); PG8_MMA(1, 0, At, B0); PG8_BAR; PG8_SCHED;
;             PG8_STAGE(PG8_SB(1, 1), b3 + hstep, voffB);
;             PG8_WAIT_V(6); PG8_BAR; PG8_MMA(1, 1, At, B1); PG8_BAR;
;             }
;         }
;         if constexpr (ALIGN_EPI) { if (wr == 0) PG8_BAR; }
	s_add_i32 s87, s87, 2
	s_add_u32 s82, s82, 0x100
	s_addc_u32 s83, s83, 0
	s_add_u32 s29, s29, 0x100
	s_addc_u32 s43, s43, 0
	s_waitcnt vmcnt(8)
	s_waitcnt lgkmcnt(0)
	s_barrier
	v_mfma_f32_16x16x32_bf16 v[60:63], v[140:143], v[184:187], v[60:63]
	v_mfma_f32_16x16x32_bf16 v[56:59], v[154:157], v[184:187], v[56:59]
	v_mfma_f32_16x16x32_bf16 v[44:47], v[140:143], v[192:195], v[44:47]
	v_mfma_f32_16x16x32_bf16 v[40:43], v[154:157], v[192:195], v[40:43]
	v_mfma_f32_16x16x32_bf16 v[28:31], v[140:143], v[222:225], v[28:31]
	v_mfma_f32_16x16x32_bf16 v[24:27], v[154:157], v[222:225], v[24:27]
	v_mfma_f32_16x16x32_bf16 v[12:15], v[140:143], v[230:233], v[12:15]
	v_mfma_f32_16x16x32_bf16 v[8:11], v[154:157], v[230:233], v[8:11]
	v_mfma_f32_16x16x32_bf16 v[60:63], v[150:153], v[188:191], v[60:63]
	v_mfma_f32_16x16x32_bf16 v[56:59], v[164:167], v[188:191], v[56:59]
	v_mfma_f32_16x16x32_bf16 v[44:47], v[150:153], v[196:199], v[44:47]
	v_mfma_f32_16x16x32_bf16 v[40:43], v[164:167], v[196:199], v[40:43]
	v_mfma_f32_16x16x32_bf16 v[28:31], v[150:153], v[226:229], v[28:31]
	v_mfma_f32_16x16x32_bf16 v[24:27], v[164:167], v[226:229], v[24:27]
	v_mfma_f32_16x16x32_bf16 v[12:15], v[150:153], v[234:237], v[12:15]
	v_mfma_f32_16x16x32_bf16 v[8:11], v[164:167], v[234:237], v[8:11]
	v_mfma_f32_16x16x32_bf16 v[52:55], v[168:171], v[184:187], v[52:55]
	v_mfma_f32_16x16x32_bf16 v[48:51], v[176:179], v[184:187], v[48:51]
	v_mfma_f32_16x16x32_bf16 v[36:39], v[168:171], v[192:195], v[36:39]
	v_mfma_f32_16x16x32_bf16 v[32:35], v[176:179], v[192:195], v[32:35]
	v_mfma_f32_16x16x32_bf16 v[20:23], v[168:171], v[222:225], v[20:23]
	v_mfma_f32_16x16x32_bf16 v[16:19], v[176:179], v[222:225], v[16:19]
	v_mfma_f32_16x16x32_bf16 v[4:7], v[168:171], v[230:233], v[4:7]
	v_mfma_f32_16x16x32_bf16 v[0:3], v[176:179], v[230:233], v[0:3]
	v_mfma_f32_16x16x32_bf16 v[52:55], v[172:175], v[188:191], v[52:55]
	v_mfma_f32_16x16x32_bf16 v[48:51], v[180:183], v[188:191], v[48:51]
	v_mfma_f32_16x16x32_bf16 v[36:39], v[172:175], v[196:199], v[36:39]
	v_mfma_f32_16x16x32_bf16 v[32:35], v[180:183], v[196:199], v[32:35]
	v_mfma_f32_16x16x32_bf16 v[20:23], v[172:175], v[226:229], v[20:23]
	v_mfma_f32_16x16x32_bf16 v[16:19], v[180:183], v[226:229], v[16:19]
	v_mfma_f32_16x16x32_bf16 v[4:7], v[172:175], v[234:237], v[4:7]
	v_mfma_f32_16x16x32_bf16 v[0:3], v[180:183], v[234:237], v[0:3]
	s_barrier
	s_cmp_gt_u32 s87, 13
	s_cbranch_scc0 .LBB0_86
	s_and_b64 vcc, exec, s[12:13]
	s_cbranch_vccz .LBB0_89
	s_barrier

; #define PG8_STAGE(bufoff, gbase, voff) do { _Pragma("unroll") for (int _i = 0; _i < 2; ++_i) \
;         __builtin_amdgcn_global_load_lds((const unsigned*)((const char*)(gbase) + (voff)[_i]), (PG8_LAS unsigned*)(lds + (bufoff) + ldsw + _i * 8192), 16, 0, 0); } while (0)
; #define PG8_LDA(dst, b, h) do { _Pragma("unroll") for (int m = 0; m < 4; ++m) _Pragma("unroll") for (int k = 0; k < 2; ++k) dst[m][k] = *(const PG8_LAS bf16x8*)(lds + PG8_SA(b, h) + aoff + m * 2048 + k * 1024); } while (0)
; #define PG8_LDB(dst, b, h) do { _Pragma("unroll") for (int n = 0; n < 2; ++n) _Pragma("unroll") for (int k = 0; k < 2; ++k) dst[n][k] = *(const PG8_LAS bf16x8*)(lds + PG8_SB(b, h) + boff + n * 2048 + k * 1024); } while (0)
; #define PG8_SCHED __builtin_amdgcn_sched_barrier(0)
; template <class Epi, class Sched, bool ALIGN_EPI = false, bool SP2 = false>
; __device__ __forceinline__ void gemm_phase(PG8_LAS unsigned char* lds, const Gemm g, const Sched& S, const Epi& E) {
;     ...
;             const bool last = (t == nt - 2);
;             const char* a1 = cA + (size_t)(t + 1) * kstep;
;             const char* a2 = last ? nA : cA + (size_t)(t + 2) * kstep; const char* b2 = last ? nB : cB + (size_t)(t + 2) * kstep;
;             const char* a3 = a2 + kstep; const char* b3 = b2 + kstep;
;             if (last && has_next) S.a_ready(nxt);
;             if constexpr (SP2) {
;             PG8_LDB(B0, 0, 0); PG8_LDB(B1, 0, 1); PG8_SCHED; PG8_LDA(At, 0, 0); PG8_STAGE(PG8_SA(1, 1), a1 + hstep, voffA);
.LBB0_322:
	s_add_i32 s56, 0, 0x10000
	s_add_i32 vcc_lo, 0, 0x14000
	s_waitcnt lgkmcnt(0)
	ds_read_b128 v[154:157], v246
	ds_read_b128 v[164:167], v246 offset:1024
	ds_read_b128 v[168:171], v246 offset:2048
	ds_read_b128 v[172:175], v246 offset:3072
	ds_read_b128 v[176:179], v246 offset:16384
	ds_read_b128 v[180:183], v246 offset:17408
	ds_read_b128 v[184:187], v246 offset:18432
	ds_read_b128 v[188:191], v246 offset:19456
	s_add_i32 m0, s89, 0xc000
	ds_read_b128 v[192:195], v145
	ds_read_b128 v[196:199], v145 offset:1024
	ds_read_b128 v[222:225], v145 offset:2048
	ds_read_b128 v[226:229], v145 offset:3072
	ds_read_b128 v[230:233], v145 offset:4096
	ds_read_b128 v[234:237], v145 offset:5120
	ds_read_b128 v[238:241], v145 offset:6144
	global_load_lds_dwordx4 v150, s[14:15]
	s_add_i32 m0, s89, 0xe000
	ds_read_b128 v[242:245], v145 offset:7168
	global_load_lds_dwordx4 v152, s[14:15]
	s_add_u32 s4, s14, 0xfff80080
	s_addc_u32 s5, s15, -1
	s_cmp_eq_u32 s55, 28
	s_cselect_b32 s53, s1, s5
	s_cselect_b32 s52, s28, s4
	s_cselect_b32 s5, s29, s54
	s_cselect_b32 s4, s43, s45

; #define PG8_STAGE(bufoff, gbase, voff) do { _Pragma("unroll") for (int _i = 0; _i < 2; ++_i) \
;         __builtin_amdgcn_global_load_lds((const unsigned*)((const char*)(gbase) + (voff)[_i]), (PG8_LAS unsigned*)(lds + (bufoff) + ldsw + _i * 8192), 16, 0, 0); } while (0)
; #define PG8_LDA(dst, b, h) do { _Pragma("unroll") for (int m = 0; m < 4; ++m) _Pragma("unroll") for (int k = 0; k < 2; ++k) dst[m][k] = *(const PG8_LAS bf16x8*)(lds + PG8_SA(b, h) + aoff + m * 2048 + k * 1024); } while (0)
; #define PG8_LDB(dst, b, h) do { _Pragma("unroll") for (int n = 0; n < 2; ++n) _Pragma("unroll") for (int k = 0; k < 2; ++k) dst[n][k] = *(const PG8_LAS bf16x8*)(lds + PG8_SB(b, h) + boff + n * 2048 + k * 1024); } while (0)
; #define PG8_MMA(ai, bj, At, Bt) do { __builtin_amdgcn_s_setprio(1); _Pragma("unroll") for (int m = 0; m < 4; ++m) _Pragma("unroll") for (int n = 0; n < 2; ++n) _Pragma("unroll") for (int k = 0; k < 2; ++k) \
;         acc[ai][bj][m][n] = __builtin_amdgcn_mfma_f32_16x16x32_bf16(Bt[n][k], At[m][k], acc[ai][bj][m][n], 0, 0, 0); __builtin_amdgcn_s_setprio(0); } while (0)
; #define PG8_WAIT_V(n) asm volatile("s_waitcnt vmcnt(" #n ")" ::: "memory")
; #define PG8_WAIT_L(n) asm volatile("s_waitcnt lgkmcnt(" #n ")" ::: "memory")
; #define PG8_BAR __builtin_amdgcn_s_barrier()
; #define PG8_SCHED __builtin_amdgcn_sched_barrier(0)
; template <class Epi, class Sched, bool ALIGN_EPI = false, bool SP2 = false>
; __device__ __forceinline__ void gemm_phase(PG8_LAS unsigned char* lds, const Gemm g, const Sched& S, const Epi& E) {
;     ...
;             PG8_LDB(B0, 0, 0); PG8_LDB(B1, 0, 1); PG8_SCHED; PG8_LDA(At, 0, 0); PG8_STAGE(PG8_SA(1, 1), a1 + hstep, voffA);
;             PG8_WAIT_V(8); PG8_WAIT_L(0); PG8_BAR; PG8_MMA(0, 0, At, B0); PG8_MMA(0, 1, At, B1); PG8_BAR; PG8_SCHED;
;             PG8_LDA(At, 0, 1); PG8_STAGE(PG8_SB(0, 0), b2, voffB); PG8_STAGE(PG8_SB(0, 1), b2 + hstep, voffB); PG8_STAGE(PG8_SA(0, 0), a2, voffA);
	s_waitcnt vmcnt(8)
	s_waitcnt lgkmcnt(0)
	s_barrier
	v_mfma_f32_16x16x32_bf16 v[124:127], v[154:157], v[192:195], v[124:127]
	v_mfma_f32_16x16x32_bf16 v[120:123], v[168:171], v[192:195], v[120:123]
	v_mfma_f32_16x16x32_bf16 v[116:119], v[154:157], v[222:225], v[116:119]
	v_mfma_f32_16x16x32_bf16 v[112:115], v[168:171], v[222:225], v[112:115]
	v_mfma_f32_16x16x32_bf16 v[108:111], v[154:157], v[230:233], v[108:111]
	v_mfma_f32_16x16x32_bf16 v[104:107], v[168:171], v[230:233], v[104:107]
	v_mfma_f32_16x16x32_bf16 v[100:103], v[154:157], v[238:241], v[100:103]
	v_mfma_f32_16x16x32_bf16 v[96:99], v[168:171], v[238:241], v[96:99]
	v_mfma_f32_16x16x32_bf16 v[124:127], v[164:167], v[196:199], v[124:127]
	v_mfma_f32_16x16x32_bf16 v[120:123], v[172:175], v[196:199], v[120:123]
	v_mfma_f32_16x16x32_bf16 v[116:119], v[164:167], v[226:229], v[116:119]
	v_mfma_f32_16x16x32_bf16 v[112:115], v[172:175], v[226:229], v[112:115]
	v_mfma_f32_16x16x32_bf16 v[108:111], v[164:167], v[234:237], v[108:111]
	v_mfma_f32_16x16x32_bf16 v[104:107], v[172:175], v[234:237], v[104:107]
	v_mfma_f32_16x16x32_bf16 v[100:103], v[164:167], v[242:245], v[100:103]
	v_mfma_f32_16x16x32_bf16 v[96:99], v[172:175], v[242:245], v[96:99]
	v_mfma_f32_16x16x32_bf16 v[92:95], v[176:179], v[192:195], v[92:95]
	v_mfma_f32_16x16x32_bf16 v[88:91], v[184:187], v[192:195], v[88:91]
	v_mfma_f32_16x16x32_bf16 v[84:87], v[176:179], v[222:225], v[84:87]
	v_mfma_f32_16x16x32_bf16 v[80:83], v[184:187], v[222:225], v[80:83]
	v_mfma_f32_16x16x32_bf16 v[76:79], v[176:179], v[230:233], v[76:79]
	v_mfma_f32_16x16x32_bf16 v[72:75], v[184:187], v[230:233], v[72:75]
	v_mfma_f32_16x16x32_bf16 v[68:71], v[176:179], v[238:241], v[68:71]
	v_mfma_f32_16x16x32_bf16 v[64:67], v[184:187], v[238:241], v[64:67]
	v_mfma_f32_16x16x32_bf16 v[92:95], v[180:183], v[196:199], v[92:95]
	v_mfma_f32_16x16x32_bf16 v[88:91], v[188:191], v[196:199], v[88:91]
	v_mfma_f32_16x16x32_bf16 v[84:87], v[180:183], v[226:229], v[84:87]
	v_mfma_f32_16x16x32_bf16 v[80:83], v[188:191], v[226:229], v[80:83]
	v_mfma_f32_16x16x32_bf16 v[76:79], v[180:183], v[234:237], v[76:79]
	v_mfma_f32_16x16x32_bf16 v[72:75], v[188:191], v[234:237], v[72:75]
	v_mfma_f32_16x16x32_bf16 v[68:71], v[180:183], v[242:245], v[68:71]
	v_mfma_f32_16x16x32_bf16 v[64:67], v[188:191], v[242:245], v[64:67]
	s_barrier
	s_add_i32 s56, s56, s63
	s_mov_b32 m0, s56
	ds_read_b128 v[192:195], v145 offset:16384
	ds_read_b128 v[196:199], v145 offset:17408
	ds_read_b128 v[222:225], v145 offset:18432
	ds_read_b128 v[226:229], v145 offset:19456
	global_load_lds_dwordx4 v130, s[4:5]
	s_add_i32 m0, s56, 0x2000
	s_add_u32 s56, s4, 0x80000
	s_addc_u32 s57, s5, 0
	s_add_i32 vcc_lo, vcc_lo, s63
	global_load_lds_dwordx4 v134, s[4:5]
	s_mov_b32 m0, vcc_lo
	ds_read_b128 v[230:233], v145 offset:20480
	global_load_lds_dwordx4 v130, s[56:57]
	s_add_i32 m0, vcc_lo, 0x2000
	ds_read_b128 v[234:237], v145 offset:21504
	global_load_lds_dwordx4 v134, s[56:57]
	s_mov_b32 m0, s89
	ds_read_b128 v[238:241], v145 offset:22528
	global_load_lds_dwordx4 v128, s[52:53]
	s_mov_b32 m0, s91
	ds_read_b128 v[242:245], v145 offset:23552
	global_load_lds_dwordx4 v132, s[52:53]
	s_add_u32 s98, s52, 0x80
	s_addc_u32 s99, s53, 0


; #define PG8_STAGE(bufoff, gbase, voff) do { _Pragma("unroll") for (int _i = 0; _i < 2; ++_i) \
;         __builtin_amdgcn_global_load_lds((const unsigned*)((const char*)(gbase) + (voff)[_i]), (PG8_LAS unsigned*)(lds + (bufoff) + ldsw + _i * 8192), 16, 0, 0); } while (0)
; #define PG8_LDA(dst, b, h) do { _Pragma("unroll") for (int m = 0; m < 4; ++m) _Pragma("unroll") for (int k = 0; k < 2; ++k) dst[m][k] = *(const PG8_LAS bf16x8*)(lds + PG8_SA(b, h) + aoff + m * 2048 + k * 1024); } while (0)
; #define PG8_LDB(dst, b, h) do { _Pragma("unroll") for (int n = 0; n < 2; ++n) _Pragma("unroll") for (int k = 0; k < 2; ++k) dst[n][k] = *(const PG8_LAS bf16x8*)(lds + PG8_SB(b, h) + boff + n * 2048 + k * 1024); } while (0)
; #define PG8_MMA(ai, bj, At, Bt) do { __builtin_amdgcn_s_setprio(1); _Pragma("unroll") for (int m = 0; m < 4; ++m) _Pragma("unroll") for (int n = 0; n < 2; ++n) _Pragma("unroll") for (int k = 0; k < 2; ++k) \
;         acc[ai][bj][m][n] = __builtin_amdgcn_mfma_f32_16x16x32_bf16(Bt[n][k], At[m][k], acc[ai][bj][m][n], 0, 0, 0); __builtin_amdgcn_s_setprio(0); } while (0)
; #define PG8_WAIT_V(n) asm volatile("s_waitcnt vmcnt(" #n ")" ::: "memory")
; #define PG8_WAIT_L(n) asm volatile("s_waitcnt lgkmcnt(" #n ")" ::: "memory")
; #define PG8_BAR __builtin_amdgcn_s_barrier()
; #define PG8_SCHED __builtin_amdgcn_sched_barrier(0)
; template <class Epi, class Sched, bool ALIGN_EPI = false, bool SP2 = false>
; __device__ __forceinline__ void gemm_phase(PG8_LAS unsigned char* lds, const Gemm g, const Sched& S, const Epi& E) {
;     ...
;             PG8_WAIT_V(8); PG8_WAIT_L(0); PG8_BAR; PG8_MMA(1, 0, At, B0); PG8_MMA(1, 1, At, B1); PG8_BAR; PG8_SCHED;
;             PG8_LDB(B0, 1, 0); PG8_LDB(B1, 1, 1); PG8_SCHED; PG8_LDA(At, 1, 0); PG8_STAGE(PG8_SA(0, 1), a2 + hstep, voffA);
	s_waitcnt vmcnt(8)
	s_waitcnt lgkmcnt(0)
	s_barrier
	v_mfma_f32_16x16x32_bf16 v[60:63], v[154:157], v[192:195], v[60:63]
	v_mfma_f32_16x16x32_bf16 v[56:59], v[168:171], v[192:195], v[56:59]
	v_mfma_f32_16x16x32_bf16 v[52:55], v[154:157], v[222:225], v[52:55]
	v_mfma_f32_16x16x32_bf16 v[48:51], v[168:171], v[222:225], v[48:51]
	v_mfma_f32_16x16x32_bf16 v[44:47], v[154:157], v[230:233], v[44:47]
	v_mfma_f32_16x16x32_bf16 v[40:43], v[168:171], v[230:233], v[40:43]
	v_mfma_f32_16x16x32_bf16 v[36:39], v[154:157], v[238:241], v[36:39]
	v_mfma_f32_16x16x32_bf16 v[32:35], v[168:171], v[238:241], v[32:35]
	v_mfma_f32_16x16x32_bf16 v[60:63], v[164:167], v[196:199], v[60:63]
	v_mfma_f32_16x16x32_bf16 v[56:59], v[172:175], v[196:199], v[56:59]
	v_mfma_f32_16x16x32_bf16 v[52:55], v[164:167], v[226:229], v[52:55]
	v_mfma_f32_16x16x32_bf16 v[48:51], v[172:175], v[226:229], v[48:51]
	v_mfma_f32_16x16x32_bf16 v[44:47], v[164:167], v[234:237], v[44:47]
	v_mfma_f32_16x16x32_bf16 v[40:43], v[172:175], v[234:237], v[40:43]
	v_mfma_f32_16x16x32_bf16 v[36:39], v[164:167], v[242:245], v[36:39]
	v_mfma_f32_16x16x32_bf16 v[32:35], v[172:175], v[242:245], v[32:35]
	v_mfma_f32_16x16x32_bf16 v[28:31], v[176:179], v[192:195], v[28:31]
	v_mfma_f32_16x16x32_bf16 v[24:27], v[184:187], v[192:195], v[24:27]
	v_mfma_f32_16x16x32_bf16 v[20:23], v[176:179], v[222:225], v[20:23]
	v_mfma_f32_16x16x32_bf16 v[16:19], v[184:187], v[222:225], v[16:19]
	v_mfma_f32_16x16x32_bf16 v[12:15], v[176:179], v[230:233], v[12:15]
	v_mfma_f32_16x16x32_bf16 v[8:11], v[184:187], v[230:233], v[8:11]
	v_mfma_f32_16x16x32_bf16 v[4:7], v[176:179], v[238:241], v[4:7]
	v_mfma_f32_16x16x32_bf16 v[0:3], v[184:187], v[238:241], v[0:3]
	v_mfma_f32_16x16x32_bf16 v[28:31], v[180:183], v[196:199], v[28:31]
	v_mfma_f32_16x16x32_bf16 v[24:27], v[188:191], v[196:199], v[24:27]
	v_mfma_f32_16x16x32_bf16 v[20:23], v[180:183], v[226:229], v[20:23]
	v_mfma_f32_16x16x32_bf16 v[16:19], v[188:191], v[226:229], v[16:19]
	v_mfma_f32_16x16x32_bf16 v[12:15], v[180:183], v[234:237], v[12:15]
	v_mfma_f32_16x16x32_bf16 v[8:11], v[188:191], v[234:237], v[8:11]
	v_mfma_f32_16x16x32_bf16 v[4:7], v[180:183], v[242:245], v[4:7]
	v_mfma_f32_16x16x32_bf16 v[0:3], v[188:191], v[242:245], v[0:3]
	s_barrier
	s_add_i32 s56, 0, 0x18000
	s_add_i32 s57, 0, 0x1c000
	ds_read_b128 v[154:157], v246 offset:32768
	ds_read_b128 v[164:167], v246 offset:33792
	ds_read_b128 v[168:171], v246 offset:34816
	ds_read_b128 v[172:175], v246 offset:35840
	ds_read_b128 v[176:179], v246 offset:49152
	ds_read_b128 v[180:183], v246 offset:50176
	ds_read_b128 v[184:187], v246 offset:51200
	ds_read_b128 v[188:191], v246 offset:52224
	s_add_u32 s52, s52, 0x80000
	s_addc_u32 s53, s53, 0
	s_mov_b32 m0, s12
	ds_read_b128 v[192:195], v145 offset:32768
	ds_read_b128 v[196:199], v145 offset:33792
	ds_read_b128 v[222:225], v145 offset:34816
	ds_read_b128 v[226:229], v145 offset:35840
	ds_read_b128 v[230:233], v145 offset:36864
	ds_read_b128 v[234:237], v145 offset:37888
	ds_read_b128 v[238:241], v145 offset:38912
	global_load_lds_dwordx4 v128, s[52:53]
	s_mov_b32 m0, s13
	ds_read_b128 v[242:245], v145 offset:39936
	global_load_lds_dwordx4 v132, s[52:53]

; #define PG8_STAGE(bufoff, gbase, voff) do { _Pragma("unroll") for (int _i = 0; _i < 2; ++_i) \
;         __builtin_amdgcn_global_load_lds((const unsigned*)((const char*)(gbase) + (voff)[_i]), (PG8_LAS unsigned*)(lds + (bufoff) + ldsw + _i * 8192), 16, 0, 0); } while (0)
; #define PG8_LDA(dst, b, h) do { _Pragma("unroll") for (int m = 0; m < 4; ++m) _Pragma("unroll") for (int k = 0; k < 2; ++k) dst[m][k] = *(const PG8_LAS bf16x8*)(lds + PG8_SA(b, h) + aoff + m * 2048 + k * 1024); } while (0)
; #define PG8_MMA(ai, bj, At, Bt) do { __builtin_amdgcn_s_setprio(1); _Pragma("unroll") for (int m = 0; m < 4; ++m) _Pragma("unroll") for (int n = 0; n < 2; ++n) _Pragma("unroll") for (int k = 0; k < 2; ++k) \
;         acc[ai][bj][m][n] = __builtin_amdgcn_mfma_f32_16x16x32_bf16(Bt[n][k], At[m][k], acc[ai][bj][m][n], 0, 0, 0); __builtin_amdgcn_s_setprio(0); } while (0)
; #define PG8_WAIT_V(n) asm volatile("s_waitcnt vmcnt(" #n ")" ::: "memory")
; #define PG8_WAIT_L(n) asm volatile("s_waitcnt lgkmcnt(" #n ")" ::: "memory")
; #define PG8_BAR __builtin_amdgcn_s_barrier()
; #define PG8_SCHED __builtin_amdgcn_sched_barrier(0)
; template <class Epi, class Sched, bool ALIGN_EPI = false, bool SP2 = false>
; __device__ __forceinline__ void gemm_phase(PG8_LAS unsigned char* lds, const Gemm g, const Sched& S, const Epi& E) {
;     ...
;             PG8_WAIT_V(8); PG8_WAIT_L(0); PG8_BAR; PG8_MMA(0, 0, At, B0); PG8_MMA(0, 1, At, B1); PG8_BAR; PG8_SCHED;
;             PG8_LDA(At, 1, 1); PG8_STAGE(PG8_SB(1, 0), b3, voffB); PG8_STAGE(PG8_SB(1, 1), b3 + hstep, voffB); PG8_STAGE(PG8_SA(1, 0), a3, voffA);
	s_waitcnt vmcnt(8)
	s_waitcnt lgkmcnt(0)
	s_barrier
	v_mfma_f32_16x16x32_bf16 v[124:127], v[154:157], v[192:195], v[124:127]
	v_mfma_f32_16x16x32_bf16 v[120:123], v[168:171], v[192:195], v[120:123]
	v_mfma_f32_16x16x32_bf16 v[116:119], v[154:157], v[222:225], v[116:119]
	v_mfma_f32_16x16x32_bf16 v[112:115], v[168:171], v[222:225], v[112:115]
	v_mfma_f32_16x16x32_bf16 v[108:111], v[154:157], v[230:233], v[108:111]
	v_mfma_f32_16x16x32_bf16 v[104:107], v[168:171], v[230:233], v[104:107]
	v_mfma_f32_16x16x32_bf16 v[100:103], v[154:157], v[238:241], v[100:103]
	v_mfma_f32_16x16x32_bf16 v[96:99], v[168:171], v[238:241], v[96:99]
	v_mfma_f32_16x16x32_bf16 v[124:127], v[164:167], v[196:199], v[124:127]
	v_mfma_f32_16x16x32_bf16 v[120:123], v[172:175], v[196:199], v[120:123]
	v_mfma_f32_16x16x32_bf16 v[116:119], v[164:167], v[226:229], v[116:119]
	v_mfma_f32_16x16x32_bf16 v[112:115], v[172:175], v[226:229], v[112:115]
	v_mfma_f32_16x16x32_bf16 v[108:111], v[164:167], v[234:237], v[108:111]
	v_mfma_f32_16x16x32_bf16 v[104:107], v[172:175], v[234:237], v[104:107]
	v_mfma_f32_16x16x32_bf16 v[100:103], v[164:167], v[242:245], v[100:103]
	v_mfma_f32_16x16x32_bf16 v[96:99], v[172:175], v[242:245], v[96:99]
	v_mfma_f32_16x16x32_bf16 v[92:95], v[176:179], v[192:195], v[92:95]
	v_mfma_f32_16x16x32_bf16 v[88:91], v[184:187], v[192:195], v[88:91]
	v_mfma_f32_16x16x32_bf16 v[84:87], v[176:179], v[222:225], v[84:87]
	v_mfma_f32_16x16x32_bf16 v[80:83], v[184:187], v[222:225], v[80:83]
	v_mfma_f32_16x16x32_bf16 v[76:79], v[176:179], v[230:233], v[76:79]
	v_mfma_f32_16x16x32_bf16 v[72:75], v[184:187], v[230:233], v[72:75]
	v_mfma_f32_16x16x32_bf16 v[68:71], v[176:179], v[238:241], v[68:71]
	v_mfma_f32_16x16x32_bf16 v[64:67], v[184:187], v[238:241], v[64:67]
	v_mfma_f32_16x16x32_bf16 v[92:95], v[180:183], v[196:199], v[92:95]
	v_mfma_f32_16x16x32_bf16 v[88:91], v[188:191], v[196:199], v[88:91]
	v_mfma_f32_16x16x32_bf16 v[84:87], v[180:183], v[226:229], v[84:87]
	v_mfma_f32_16x16x32_bf16 v[80:83], v[188:191], v[226:229], v[80:83]
	v_mfma_f32_16x16x32_bf16 v[76:79], v[180:183], v[234:237], v[76:79]
	v_mfma_f32_16x16x32_bf16 v[72:75], v[188:191], v[234:237], v[72:75]
	v_mfma_f32_16x16x32_bf16 v[68:71], v[180:183], v[242:245], v[68:71]
	v_mfma_f32_16x16x32_bf16 v[64:67], v[188:191], v[242:245], v[64:67]
	s_barrier
	s_add_i32 s52, s56, s63
	s_mov_b32 m0, s52
	ds_read_b128 v[192:195], v145 offset:49152
	ds_read_b128 v[196:199], v145 offset:50176
	ds_read_b128 v[222:225], v145 offset:51200
	ds_read_b128 v[226:229], v145 offset:52224
	s_add_u32 s4, s4, 0x80
	s_addc_u32 s5, s5, 0
	global_load_lds_dwordx4 v130, s[4:5]
	s_add_i32 m0, s52, 0x2000
	s_add_i32 s52, s57, s63
	global_load_lds_dwordx4 v134, s[4:5]
	s_add_u32 s4, s4, 0x80000
	s_addc_u32 s5, s5, 0
	s_mov_b32 m0, s52
	ds_read_b128 v[230:233], v145 offset:53248
	global_load_lds_dwordx4 v130, s[4:5]
	s_add_i32 m0, s52, 0x2000
	ds_read_b128 v[234:237], v145 offset:54272
	global_load_lds_dwordx4 v134, s[4:5]
	s_mov_b32 m0, s78
	ds_read_b128 v[238:241], v145 offset:55296
	global_load_lds_dwordx4 v128, s[98:99]
	s_mov_b32 m0, s79
	ds_read_b128 v[242:245], v145 offset:56320
	global_load_lds_dwordx4 v132, s[98:99]


; #define PG8_STAGE(bufoff, gbase, voff) do { _Pragma("unroll") for (int _i = 0; _i < 2; ++_i) \
;         __builtin_amdgcn_global_load_lds((const unsigned*)((const char*)(gbase) + (voff)[_i]), (PG8_LAS unsigned*)(lds + (bufoff) + ldsw + _i * 8192), 16, 0, 0); } while (0)
; #define PG8_LDA(dst, b, h) do { _Pragma("unroll") for (int m = 0; m < 4; ++m) _Pragma("unroll") for (int k = 0; k < 2; ++k) dst[m][k] = *(const PG8_LAS bf16x8*)(lds + PG8_SA(b, h) + aoff + m * 2048 + k * 1024); } while (0)
; #define PG8_LDB(dst, b, h) do { _Pragma("unroll") for (int n = 0; n < 2; ++n) _Pragma("unroll") for (int k = 0; k < 2; ++k) dst[n][k] = *(const PG8_LAS bf16x8*)(lds + PG8_SB(b, h) + boff + n * 2048 + k * 1024); } while (0)
; template <class Epi, class Sched, bool ALIGN_EPI = false, bool SP2 = false>
; __device__ __forceinline__ void gemm_phase(PG8_LAS unsigned char* lds, const Gemm g, const Sched& S, const Epi& E) {
;     ...
;             PG8_WAIT_V(8); PG8_WAIT_L(0); PG8_BAR; PG8_MMA(1, 0, At, B0); PG8_MMA(1, 1, At, B1); PG8_BAR; PG8_SCHED;
;             } else {
;             PG8_LDB(B0, 0, 0); PG8_SCHED; PG8_LDA(At, 0, 0); PG8_STAGE(PG8_SA(1, 1), a1 + hstep, voffA);
;             PG8_WAIT_L(8); PG8_BAR; PG8_WAIT_L(0); PG8_MMA(0, 0, At, B0); PG8_BAR; PG8_SCHED;
;             PG8_LDB(B1, 0, 1); PG8_STAGE(PG8_SB(0, 0), b2, voffB);
;             PG8_BAR; PG8_WAIT_L(0); PG8_MMA(0, 1, At, B1); PG8_BAR;
;             PG8_LDA(At, 0, 1); PG8_STAGE(PG8_SA(0, 0), a2, voffA);
;             PG8_BAR; PG8_WAIT_L(0); PG8_MMA(1, 0, At, B0); PG8_BAR; PG8_SCHED;
;             PG8_STAGE(PG8_SB(0, 1), b2 + hstep, voffB);
;             PG8_WAIT_V(6); PG8_BAR; PG8_MMA(1, 1, At, B1); PG8_BAR;
;             PG8_LDB(B0, 1, 0); PG8_SCHED; PG8_LDA(At, 1, 0); PG8_STAGE(PG8_SA(0, 1), a2 + hstep, voffA);
;             PG8_WAIT_L(8); PG8_BAR; PG8_WAIT_L(0); PG8_MMA(0, 0, At, B0); PG8_BAR; PG8_SCHED;
;             PG8_LDB(B1, 1, 1); PG8_STAGE(PG8_SB(1, 0), b3, voffB);
;             PG8_BAR; PG8_WAIT_L(0); PG8_MMA(0, 1, At, B1); PG8_BAR;
;             PG8_LDA(At, 1, 1); PG8_STAGE(PG8_SA(1, 0), a3, voffA);
;             PG8_BAR; PG8_WAIT_L(0); PG8_MMA(1, 0, At, B0); PG8_BAR; PG8_SCHED;
;             PG8_STAGE(PG8_SB(1, 1), b3 + hstep, voffB);
;             PG8_WAIT_V(6); PG8_BAR; PG8_MMA(1, 1, At, B1); PG8_BAR;
;             }
;         }
;         if constexpr (ALIGN_EPI) { if (wr == 0) PG8_BAR; }
	s_add_i32 s55, s55, 2
	s_add_u32 s14, s14, 0x100
	s_addc_u32 s15, s15, 0
	s_add_u32 s45, s45, 0x100
	s_addc_u32 s54, s54, 0
	s_waitcnt vmcnt(8)
	s_waitcnt lgkmcnt(0)
	s_barrier
	v_mfma_f32_16x16x32_bf16 v[60:63], v[154:157], v[192:195], v[60:63]
	v_mfma_f32_16x16x32_bf16 v[56:59], v[168:171], v[192:195], v[56:59]
	v_mfma_f32_16x16x32_bf16 v[52:55], v[154:157], v[222:225], v[52:55]
	v_mfma_f32_16x16x32_bf16 v[48:51], v[168:171], v[222:225], v[48:51]
	v_mfma_f32_16x16x32_bf16 v[44:47], v[154:157], v[230:233], v[44:47]
	v_mfma_f32_16x16x32_bf16 v[40:43], v[168:171], v[230:233], v[40:43]
	v_mfma_f32_16x16x32_bf16 v[36:39], v[154:157], v[238:241], v[36:39]
	v_mfma_f32_16x16x32_bf16 v[32:35], v[168:171], v[238:241], v[32:35]
	v_mfma_f32_16x16x32_bf16 v[60:63], v[164:167], v[196:199], v[60:63]
	v_mfma_f32_16x16x32_bf16 v[56:59], v[172:175], v[196:199], v[56:59]
	v_mfma_f32_16x16x32_bf16 v[52:55], v[164:167], v[226:229], v[52:55]
	v_mfma_f32_16x16x32_bf16 v[48:51], v[172:175], v[226:229], v[48:51]
	v_mfma_f32_16x16x32_bf16 v[44:47], v[164:167], v[234:237], v[44:47]
	v_mfma_f32_16x16x32_bf16 v[40:43], v[172:175], v[234:237], v[40:43]
	v_mfma_f32_16x16x32_bf16 v[36:39], v[164:167], v[242:245], v[36:39]
	v_mfma_f32_16x16x32_bf16 v[32:35], v[172:175], v[242:245], v[32:35]
	v_mfma_f32_16x16x32_bf16 v[28:31], v[176:179], v[192:195], v[28:31]
	v_mfma_f32_16x16x32_bf16 v[24:27], v[184:187], v[192:195], v[24:27]
	v_mfma_f32_16x16x32_bf16 v[20:23], v[176:179], v[222:225], v[20:23]
	v_mfma_f32_16x16x32_bf16 v[16:19], v[184:187], v[222:225], v[16:19]
	v_mfma_f32_16x16x32_bf16 v[12:15], v[176:179], v[230:233], v[12:15]
	v_mfma_f32_16x16x32_bf16 v[8:11], v[184:187], v[230:233], v[8:11]
	v_mfma_f32_16x16x32_bf16 v[4:7], v[176:179], v[238:241], v[4:7]
	v_mfma_f32_16x16x32_bf16 v[0:3], v[184:187], v[238:241], v[0:3]
	v_mfma_f32_16x16x32_bf16 v[28:31], v[180:183], v[196:199], v[28:31]
	v_mfma_f32_16x16x32_bf16 v[24:27], v[188:191], v[196:199], v[24:27]
	v_mfma_f32_16x16x32_bf16 v[20:23], v[180:183], v[226:229], v[20:23]
	v_mfma_f32_16x16x32_bf16 v[16:19], v[188:191], v[226:229], v[16:19]
	v_mfma_f32_16x16x32_bf16 v[12:15], v[180:183], v[234:237], v[12:15]
	v_mfma_f32_16x16x32_bf16 v[8:11], v[188:191], v[234:237], v[8:11]
	v_mfma_f32_16x16x32_bf16 v[4:7], v[180:183], v[242:245], v[4:7]
	v_mfma_f32_16x16x32_bf16 v[0:3], v[188:191], v[242:245], v[0:3]
	s_barrier
	s_cmp_gt_u32 s55, 29
	s_cbranch_scc0 .LBB0_322
	s_and_b64 vcc, exec, s[82:83]
	s_cbranch_vccz .LBB0_325
	s_barrier

; #define PG8_STAGE(bufoff, gbase, voff) do { _Pragma("unroll") for (int _i = 0; _i < 2; ++_i) \
;         __builtin_amdgcn_global_load_lds((const unsigned*)((const char*)(gbase) + (voff)[_i]), (PG8_LAS unsigned*)(lds + (bufoff) + ldsw + _i * 8192), 16, 0, 0); } while (0)
; #define PG8_LDA(dst, b, h) do { _Pragma("unroll") for (int m = 0; m < 4; ++m) _Pragma("unroll") for (int k = 0; k < 2; ++k) dst[m][k] = *(const PG8_LAS bf16x8*)(lds + PG8_SA(b, h) + aoff + m * 2048 + k * 1024); } while (0)
; #define PG8_LDB(dst, b, h) do { _Pragma("unroll") for (int n = 0; n < 2; ++n) _Pragma("unroll") for (int k = 0; k < 2; ++k) dst[n][k] = *(const PG8_LAS bf16x8*)(lds + PG8_SB(b, h) + boff + n * 2048 + k * 1024); } while (0)
; #define PG8_SCHED __builtin_amdgcn_sched_barrier(0)
; template <class Epi, class Sched, bool ALIGN_EPI = false, bool SP2 = false>
; __device__ __forceinline__ void gemm_phase(PG8_LAS unsigned char* lds, const Gemm g, const Sched& S, const Epi& E) {
;     ...
;             const bool last = (t == nt - 2);
;             const char* a1 = cA + (size_t)(t + 1) * kstep;
;             const char* a2 = last ? nA : cA + (size_t)(t + 2) * kstep; const char* b2 = last ? nB : cB + (size_t)(t + 2) * kstep;
;             const char* a3 = a2 + kstep; const char* b3 = b2 + kstep;
;             if (last && has_next) S.a_ready(nxt);
;             if constexpr (SP2) {
;             PG8_LDB(B0, 0, 0); PG8_LDB(B1, 0, 1); PG8_SCHED; PG8_LDA(At, 0, 0); PG8_STAGE(PG8_SA(1, 1), a1 + hstep, voffA);
.LBB0_849:
	s_add_i32 s76, 0, 0x10000
	s_add_i32 s78, 0, 0x14000
	ds_read_b128 v[144:147], v200
	ds_read_b128 v[148:151], v200 offset:1024
	ds_read_b128 v[152:155], v200 offset:2048
	ds_read_b128 v[156:159], v200 offset:3072
	ds_read_b128 v[164:167], v200 offset:16384
	ds_read_b128 v[168:171], v200 offset:17408
	ds_read_b128 v[172:175], v200 offset:18432
	ds_read_b128 v[176:179], v200 offset:19456
	s_add_i32 m0, s51, 0xc000
	ds_read_b128 v[180:183], v143
	ds_read_b128 v[184:187], v143 offset:1024
	ds_read_b128 v[188:191], v143 offset:2048
	ds_read_b128 v[192:195], v143 offset:3072
	ds_read_b128 v[196:199], v143 offset:4096
	ds_read_b128 v[222:225], v143 offset:5120
	ds_read_b128 v[226:229], v143 offset:6144
	global_load_lds_dwordx4 v134, s[70:71]
	s_add_i32 m0, s51, 0xe000
	ds_read_b128 v[230:233], v143 offset:7168
	global_load_lds_dwordx4 v136, s[70:71]
	s_add_u32 s4, s70, 0xfff80080
	s_addc_u32 s5, s71, -1
	s_cmp_eq_u32 s75, 28
	s_cselect_b32 s53, s11, s5
	s_cselect_b32 s52, s63, s4
	s_cselect_b32 s5, s13, s74
	s_cselect_b32 s4, s72, s73

; #define PG8_STAGE(bufoff, gbase, voff) do { _Pragma("unroll") for (int _i = 0; _i < 2; ++_i) \
;         __builtin_amdgcn_global_load_lds((const unsigned*)((const char*)(gbase) + (voff)[_i]), (PG8_LAS unsigned*)(lds + (bufoff) + ldsw + _i * 8192), 16, 0, 0); } while (0)
; #define PG8_LDA(dst, b, h) do { _Pragma("unroll") for (int m = 0; m < 4; ++m) _Pragma("unroll") for (int k = 0; k < 2; ++k) dst[m][k] = *(const PG8_LAS bf16x8*)(lds + PG8_SA(b, h) + aoff + m * 2048 + k * 1024); } while (0)
; #define PG8_LDB(dst, b, h) do { _Pragma("unroll") for (int n = 0; n < 2; ++n) _Pragma("unroll") for (int k = 0; k < 2; ++k) dst[n][k] = *(const PG8_LAS bf16x8*)(lds + PG8_SB(b, h) + boff + n * 2048 + k * 1024); } while (0)
; #define PG8_MMA(ai, bj, At, Bt) do { __builtin_amdgcn_s_setprio(1); _Pragma("unroll") for (int m = 0; m < 4; ++m) _Pragma("unroll") for (int n = 0; n < 2; ++n) _Pragma("unroll") for (int k = 0; k < 2; ++k) \
;         acc[ai][bj][m][n] = __builtin_amdgcn_mfma_f32_16x16x32_bf16(Bt[n][k], At[m][k], acc[ai][bj][m][n], 0, 0, 0); __builtin_amdgcn_s_setprio(0); } while (0)
; #define PG8_WAIT_V(n) asm volatile("s_waitcnt vmcnt(" #n ")" ::: "memory")
; #define PG8_WAIT_L(n) asm volatile("s_waitcnt lgkmcnt(" #n ")" ::: "memory")
; #define PG8_BAR __builtin_amdgcn_s_barrier()
; #define PG8_SCHED __builtin_amdgcn_sched_barrier(0)
; template <class Epi, class Sched, bool ALIGN_EPI = false, bool SP2 = false>
; __device__ __forceinline__ void gemm_phase(PG8_LAS unsigned char* lds, const Gemm g, const Sched& S, const Epi& E) {
;     ...
;             PG8_LDB(B0, 0, 0); PG8_LDB(B1, 0, 1); PG8_SCHED; PG8_LDA(At, 0, 0); PG8_STAGE(PG8_SA(1, 1), a1 + hstep, voffA);
;             PG8_WAIT_V(8); PG8_WAIT_L(0); PG8_BAR; PG8_MMA(0, 0, At, B0); PG8_MMA(0, 1, At, B1); PG8_BAR; PG8_SCHED;
;             PG8_LDA(At, 0, 1); PG8_STAGE(PG8_SB(0, 0), b2, voffB); PG8_STAGE(PG8_SB(0, 1), b2 + hstep, voffB); PG8_STAGE(PG8_SA(0, 0), a2, voffA);
	s_waitcnt vmcnt(8)
	s_waitcnt lgkmcnt(0)
	s_barrier
	v_mfma_f32_16x16x32_bf16 v[124:127], v[144:147], v[180:183], v[124:127]
	v_mfma_f32_16x16x32_bf16 v[116:119], v[152:155], v[180:183], v[116:119]
	v_mfma_f32_16x16x32_bf16 v[108:111], v[144:147], v[188:191], v[108:111]
	v_mfma_f32_16x16x32_bf16 v[100:103], v[152:155], v[188:191], v[100:103]
	v_mfma_f32_16x16x32_bf16 v[92:95], v[144:147], v[196:199], v[92:95]
	v_mfma_f32_16x16x32_bf16 v[84:87], v[152:155], v[196:199], v[84:87]
	v_mfma_f32_16x16x32_bf16 v[76:79], v[144:147], v[226:229], v[76:79]
	v_mfma_f32_16x16x32_bf16 v[68:71], v[152:155], v[226:229], v[68:71]
	v_mfma_f32_16x16x32_bf16 v[124:127], v[148:151], v[184:187], v[124:127]
	v_mfma_f32_16x16x32_bf16 v[116:119], v[156:159], v[184:187], v[116:119]
	v_mfma_f32_16x16x32_bf16 v[108:111], v[148:151], v[192:195], v[108:111]
	v_mfma_f32_16x16x32_bf16 v[100:103], v[156:159], v[192:195], v[100:103]
	v_mfma_f32_16x16x32_bf16 v[92:95], v[148:151], v[222:225], v[92:95]
	v_mfma_f32_16x16x32_bf16 v[84:87], v[156:159], v[222:225], v[84:87]
	v_mfma_f32_16x16x32_bf16 v[76:79], v[148:151], v[230:233], v[76:79]
	v_mfma_f32_16x16x32_bf16 v[68:71], v[156:159], v[230:233], v[68:71]
	v_mfma_f32_16x16x32_bf16 v[120:123], v[164:167], v[180:183], v[120:123]
	v_mfma_f32_16x16x32_bf16 v[112:115], v[172:175], v[180:183], v[112:115]
	v_mfma_f32_16x16x32_bf16 v[104:107], v[164:167], v[188:191], v[104:107]
	v_mfma_f32_16x16x32_bf16 v[96:99], v[172:175], v[188:191], v[96:99]
	v_mfma_f32_16x16x32_bf16 v[88:91], v[164:167], v[196:199], v[88:91]
	v_mfma_f32_16x16x32_bf16 v[80:83], v[172:175], v[196:199], v[80:83]
	v_mfma_f32_16x16x32_bf16 v[72:75], v[164:167], v[226:229], v[72:75]
	v_mfma_f32_16x16x32_bf16 v[64:67], v[172:175], v[226:229], v[64:67]
	v_mfma_f32_16x16x32_bf16 v[120:123], v[168:171], v[184:187], v[120:123]
	v_mfma_f32_16x16x32_bf16 v[112:115], v[176:179], v[184:187], v[112:115]
	v_mfma_f32_16x16x32_bf16 v[104:107], v[168:171], v[192:195], v[104:107]
	v_mfma_f32_16x16x32_bf16 v[96:99], v[176:179], v[192:195], v[96:99]
	v_mfma_f32_16x16x32_bf16 v[88:91], v[168:171], v[222:225], v[88:91]
	v_mfma_f32_16x16x32_bf16 v[80:83], v[176:179], v[222:225], v[80:83]
	v_mfma_f32_16x16x32_bf16 v[72:75], v[168:171], v[230:233], v[72:75]
	v_mfma_f32_16x16x32_bf16 v[64:67], v[176:179], v[230:233], v[64:67]
	s_barrier
	s_add_i32 s76, s76, s24
	s_mov_b32 m0, s76
	ds_read_b128 v[180:183], v143 offset:16384
	ds_read_b128 v[184:187], v143 offset:17408
	ds_read_b128 v[188:191], v143 offset:18432
	ds_read_b128 v[192:195], v143 offset:19456
	global_load_lds_dwordx4 v160, s[4:5]
	s_add_i32 m0, s76, 0x2000
	s_add_u32 s76, s4, 0x80000
	s_addc_u32 s77, s5, 0
	s_add_i32 s78, s78, s24
	global_load_lds_dwordx4 v128, s[4:5]
	s_mov_b32 m0, s78
	ds_read_b128 v[196:199], v143 offset:20480
	global_load_lds_dwordx4 v160, s[76:77]
	s_add_i32 m0, s78, 0x2000
	ds_read_b128 v[222:225], v143 offset:21504
	global_load_lds_dwordx4 v128, s[76:77]
	s_mov_b32 m0, s51
	ds_read_b128 v[226:229], v143 offset:22528
	global_load_lds_dwordx4 v132, s[52:53]
	s_mov_b32 m0, s55
	ds_read_b128 v[230:233], v143 offset:23552
	global_load_lds_dwordx4 v130, s[52:53]
	s_add_u32 s98, s52, 0x80
	s_addc_u32 s99, s53, 0


; #define PG8_STAGE(bufoff, gbase, voff) do { _Pragma("unroll") for (int _i = 0; _i < 2; ++_i) \
;         __builtin_amdgcn_global_load_lds((const unsigned*)((const char*)(gbase) + (voff)[_i]), (PG8_LAS unsigned*)(lds + (bufoff) + ldsw + _i * 8192), 16, 0, 0); } while (0)
; #define PG8_LDA(dst, b, h) do { _Pragma("unroll") for (int m = 0; m < 4; ++m) _Pragma("unroll") for (int k = 0; k < 2; ++k) dst[m][k] = *(const PG8_LAS bf16x8*)(lds + PG8_SA(b, h) + aoff + m * 2048 + k * 1024); } while (0)
; #define PG8_LDB(dst, b, h) do { _Pragma("unroll") for (int n = 0; n < 2; ++n) _Pragma("unroll") for (int k = 0; k < 2; ++k) dst[n][k] = *(const PG8_LAS bf16x8*)(lds + PG8_SB(b, h) + boff + n * 2048 + k * 1024); } while (0)
; #define PG8_MMA(ai, bj, At, Bt) do { __builtin_amdgcn_s_setprio(1); _Pragma("unroll") for (int m = 0; m < 4; ++m) _Pragma("unroll") for (int n = 0; n < 2; ++n) _Pragma("unroll") for (int k = 0; k < 2; ++k) \
;         acc[ai][bj][m][n] = __builtin_amdgcn_mfma_f32_16x16x32_bf16(Bt[n][k], At[m][k], acc[ai][bj][m][n], 0, 0, 0); __builtin_amdgcn_s_setprio(0); } while (0)
; #define PG8_WAIT_V(n) asm volatile("s_waitcnt vmcnt(" #n ")" ::: "memory")
; #define PG8_WAIT_L(n) asm volatile("s_waitcnt lgkmcnt(" #n ")" ::: "memory")
; #define PG8_BAR __builtin_amdgcn_s_barrier()
; #define PG8_SCHED __builtin_amdgcn_sched_barrier(0)
; template <class Epi, class Sched, bool ALIGN_EPI = false, bool SP2 = false>
; __device__ __forceinline__ void gemm_phase(PG8_LAS unsigned char* lds, const Gemm g, const Sched& S, const Epi& E) {
;     ...
;             PG8_WAIT_V(8); PG8_WAIT_L(0); PG8_BAR; PG8_MMA(1, 0, At, B0); PG8_MMA(1, 1, At, B1); PG8_BAR; PG8_SCHED;
;             PG8_LDB(B0, 1, 0); PG8_LDB(B1, 1, 1); PG8_SCHED; PG8_LDA(At, 1, 0); PG8_STAGE(PG8_SA(0, 1), a2 + hstep, voffA);
	s_waitcnt vmcnt(8)
	s_waitcnt lgkmcnt(0)
	s_barrier
	v_mfma_f32_16x16x32_bf16 v[60:63], v[144:147], v[180:183], v[60:63]
	v_mfma_f32_16x16x32_bf16 v[52:55], v[152:155], v[180:183], v[52:55]
	v_mfma_f32_16x16x32_bf16 v[44:47], v[144:147], v[188:191], v[44:47]
	v_mfma_f32_16x16x32_bf16 v[36:39], v[152:155], v[188:191], v[36:39]
	v_mfma_f32_16x16x32_bf16 v[28:31], v[144:147], v[196:199], v[28:31]
	v_mfma_f32_16x16x32_bf16 v[20:23], v[152:155], v[196:199], v[20:23]
	v_mfma_f32_16x16x32_bf16 v[12:15], v[144:147], v[226:229], v[12:15]
	v_mfma_f32_16x16x32_bf16 v[4:7], v[152:155], v[226:229], v[4:7]
	v_mfma_f32_16x16x32_bf16 v[60:63], v[148:151], v[184:187], v[60:63]
	v_mfma_f32_16x16x32_bf16 v[52:55], v[156:159], v[184:187], v[52:55]
	v_mfma_f32_16x16x32_bf16 v[44:47], v[148:151], v[192:195], v[44:47]
	v_mfma_f32_16x16x32_bf16 v[36:39], v[156:159], v[192:195], v[36:39]
	v_mfma_f32_16x16x32_bf16 v[28:31], v[148:151], v[222:225], v[28:31]
	v_mfma_f32_16x16x32_bf16 v[20:23], v[156:159], v[222:225], v[20:23]
	v_mfma_f32_16x16x32_bf16 v[12:15], v[148:151], v[230:233], v[12:15]
	v_mfma_f32_16x16x32_bf16 v[4:7], v[156:159], v[230:233], v[4:7]
	v_mfma_f32_16x16x32_bf16 v[56:59], v[164:167], v[180:183], v[56:59]
	v_mfma_f32_16x16x32_bf16 v[48:51], v[172:175], v[180:183], v[48:51]
	v_mfma_f32_16x16x32_bf16 v[40:43], v[164:167], v[188:191], v[40:43]
	v_mfma_f32_16x16x32_bf16 v[32:35], v[172:175], v[188:191], v[32:35]
	v_mfma_f32_16x16x32_bf16 v[24:27], v[164:167], v[196:199], v[24:27]
	v_mfma_f32_16x16x32_bf16 v[16:19], v[172:175], v[196:199], v[16:19]
	v_mfma_f32_16x16x32_bf16 v[8:11], v[164:167], v[226:229], v[8:11]
	v_mfma_f32_16x16x32_bf16 v[0:3], v[172:175], v[226:229], v[0:3]
	v_mfma_f32_16x16x32_bf16 v[56:59], v[168:171], v[184:187], v[56:59]
	v_mfma_f32_16x16x32_bf16 v[48:51], v[176:179], v[184:187], v[48:51]
	v_mfma_f32_16x16x32_bf16 v[40:43], v[168:171], v[192:195], v[40:43]
	v_mfma_f32_16x16x32_bf16 v[32:35], v[176:179], v[192:195], v[32:35]
	v_mfma_f32_16x16x32_bf16 v[24:27], v[168:171], v[222:225], v[24:27]
	v_mfma_f32_16x16x32_bf16 v[16:19], v[176:179], v[222:225], v[16:19]
	v_mfma_f32_16x16x32_bf16 v[8:11], v[168:171], v[230:233], v[8:11]
	v_mfma_f32_16x16x32_bf16 v[0:3], v[176:179], v[230:233], v[0:3]
	s_barrier
	s_add_i32 s76, 0, 0x18000
	s_add_i32 s77, 0, 0x1c000
	ds_read_b128 v[144:147], v200 offset:32768
	ds_read_b128 v[148:151], v200 offset:33792
	ds_read_b128 v[152:155], v200 offset:34816
	ds_read_b128 v[156:159], v200 offset:35840
	ds_read_b128 v[164:167], v200 offset:49152
	ds_read_b128 v[168:171], v200 offset:50176
	ds_read_b128 v[172:175], v200 offset:51200
	ds_read_b128 v[176:179], v200 offset:52224
	s_add_u32 s52, s52, 0x80000
	s_addc_u32 s53, s53, 0
	s_mov_b32 m0, s56
	ds_read_b128 v[180:183], v143 offset:32768
	ds_read_b128 v[184:187], v143 offset:33792
	ds_read_b128 v[188:191], v143 offset:34816
	ds_read_b128 v[192:195], v143 offset:35840
	ds_read_b128 v[196:199], v143 offset:36864
	ds_read_b128 v[222:225], v143 offset:37888
	ds_read_b128 v[226:229], v143 offset:38912
	global_load_lds_dwordx4 v132, s[52:53]
	s_mov_b32 m0, s57
	ds_read_b128 v[230:233], v143 offset:39936
	global_load_lds_dwordx4 v130, s[52:53]

; #define PG8_STAGE(bufoff, gbase, voff) do { _Pragma("unroll") for (int _i = 0; _i < 2; ++_i) \
;         __builtin_amdgcn_global_load_lds((const unsigned*)((const char*)(gbase) + (voff)[_i]), (PG8_LAS unsigned*)(lds + (bufoff) + ldsw + _i * 8192), 16, 0, 0); } while (0)
; #define PG8_LDA(dst, b, h) do { _Pragma("unroll") for (int m = 0; m < 4; ++m) _Pragma("unroll") for (int k = 0; k < 2; ++k) dst[m][k] = *(const PG8_LAS bf16x8*)(lds + PG8_SA(b, h) + aoff + m * 2048 + k * 1024); } while (0)
; #define PG8_MMA(ai, bj, At, Bt) do { __builtin_amdgcn_s_setprio(1); _Pragma("unroll") for (int m = 0; m < 4; ++m) _Pragma("unroll") for (int n = 0; n < 2; ++n) _Pragma("unroll") for (int k = 0; k < 2; ++k) \
;         acc[ai][bj][m][n] = __builtin_amdgcn_mfma_f32_16x16x32_bf16(Bt[n][k], At[m][k], acc[ai][bj][m][n], 0, 0, 0); __builtin_amdgcn_s_setprio(0); } while (0)
; #define PG8_WAIT_V(n) asm volatile("s_waitcnt vmcnt(" #n ")" ::: "memory")
; #define PG8_WAIT_L(n) asm volatile("s_waitcnt lgkmcnt(" #n ")" ::: "memory")
; #define PG8_BAR __builtin_amdgcn_s_barrier()
; #define PG8_SCHED __builtin_amdgcn_sched_barrier(0)
; template <class Epi, class Sched, bool ALIGN_EPI = false, bool SP2 = false>
; __device__ __forceinline__ void gemm_phase(PG8_LAS unsigned char* lds, const Gemm g, const Sched& S, const Epi& E) {
;     ...
;             PG8_WAIT_V(8); PG8_WAIT_L(0); PG8_BAR; PG8_MMA(0, 0, At, B0); PG8_MMA(0, 1, At, B1); PG8_BAR; PG8_SCHED;
;             PG8_LDA(At, 1, 1); PG8_STAGE(PG8_SB(1, 0), b3, voffB); PG8_STAGE(PG8_SB(1, 1), b3 + hstep, voffB); PG8_STAGE(PG8_SA(1, 0), a3, voffA);
	s_waitcnt vmcnt(8)
	s_waitcnt lgkmcnt(0)
	s_barrier
	v_mfma_f32_16x16x32_bf16 v[124:127], v[144:147], v[180:183], v[124:127]
	v_mfma_f32_16x16x32_bf16 v[116:119], v[152:155], v[180:183], v[116:119]
	v_mfma_f32_16x16x32_bf16 v[108:111], v[144:147], v[188:191], v[108:111]
	v_mfma_f32_16x16x32_bf16 v[100:103], v[152:155], v[188:191], v[100:103]
	v_mfma_f32_16x16x32_bf16 v[92:95], v[144:147], v[196:199], v[92:95]
	v_mfma_f32_16x16x32_bf16 v[84:87], v[152:155], v[196:199], v[84:87]
	v_mfma_f32_16x16x32_bf16 v[76:79], v[144:147], v[226:229], v[76:79]
	v_mfma_f32_16x16x32_bf16 v[68:71], v[152:155], v[226:229], v[68:71]
	v_mfma_f32_16x16x32_bf16 v[124:127], v[148:151], v[184:187], v[124:127]
	v_mfma_f32_16x16x32_bf16 v[116:119], v[156:159], v[184:187], v[116:119]
	v_mfma_f32_16x16x32_bf16 v[108:111], v[148:151], v[192:195], v[108:111]
	v_mfma_f32_16x16x32_bf16 v[100:103], v[156:159], v[192:195], v[100:103]
	v_mfma_f32_16x16x32_bf16 v[92:95], v[148:151], v[222:225], v[92:95]
	v_mfma_f32_16x16x32_bf16 v[84:87], v[156:159], v[222:225], v[84:87]
	v_mfma_f32_16x16x32_bf16 v[76:79], v[148:151], v[230:233], v[76:79]
	v_mfma_f32_16x16x32_bf16 v[68:71], v[156:159], v[230:233], v[68:71]
	v_mfma_f32_16x16x32_bf16 v[120:123], v[164:167], v[180:183], v[120:123]
	v_mfma_f32_16x16x32_bf16 v[112:115], v[172:175], v[180:183], v[112:115]
	v_mfma_f32_16x16x32_bf16 v[104:107], v[164:167], v[188:191], v[104:107]
	v_mfma_f32_16x16x32_bf16 v[96:99], v[172:175], v[188:191], v[96:99]
	v_mfma_f32_16x16x32_bf16 v[88:91], v[164:167], v[196:199], v[88:91]
	v_mfma_f32_16x16x32_bf16 v[80:83], v[172:175], v[196:199], v[80:83]
	v_mfma_f32_16x16x32_bf16 v[72:75], v[164:167], v[226:229], v[72:75]
	v_mfma_f32_16x16x32_bf16 v[64:67], v[172:175], v[226:229], v[64:67]
	v_mfma_f32_16x16x32_bf16 v[120:123], v[168:171], v[184:187], v[120:123]
	v_mfma_f32_16x16x32_bf16 v[112:115], v[176:179], v[184:187], v[112:115]
	v_mfma_f32_16x16x32_bf16 v[104:107], v[168:171], v[192:195], v[104:107]
	v_mfma_f32_16x16x32_bf16 v[96:99], v[176:179], v[192:195], v[96:99]
	v_mfma_f32_16x16x32_bf16 v[88:91], v[168:171], v[222:225], v[88:91]
	v_mfma_f32_16x16x32_bf16 v[80:83], v[176:179], v[222:225], v[80:83]
	v_mfma_f32_16x16x32_bf16 v[72:75], v[168:171], v[230:233], v[72:75]
	v_mfma_f32_16x16x32_bf16 v[64:67], v[176:179], v[230:233], v[64:67]
	s_barrier
	s_add_i32 s52, s76, s24
	s_mov_b32 m0, s52
	ds_read_b128 v[180:183], v143 offset:49152
	ds_read_b128 v[184:187], v143 offset:50176
	ds_read_b128 v[188:191], v143 offset:51200
	ds_read_b128 v[192:195], v143 offset:52224
	s_add_u32 s4, s4, 0x80
	s_addc_u32 s5, s5, 0
	global_load_lds_dwordx4 v160, s[4:5]
	s_add_i32 m0, s52, 0x2000
	s_add_i32 s52, s77, s24
	global_load_lds_dwordx4 v128, s[4:5]
	s_add_u32 s4, s4, 0x80000
	s_addc_u32 s5, s5, 0
	s_mov_b32 m0, s52
	ds_read_b128 v[196:199], v143 offset:53248
	global_load_lds_dwordx4 v160, s[4:5]
	s_add_i32 m0, s52, 0x2000
	ds_read_b128 v[222:225], v143 offset:54272
	global_load_lds_dwordx4 v128, s[4:5]
	s_mov_b32 m0, s58
	ds_read_b128 v[226:229], v143 offset:55296
	global_load_lds_dwordx4 v132, s[98:99]
	s_mov_b32 m0, s59
	ds_read_b128 v[230:233], v143 offset:56320
	global_load_lds_dwordx4 v130, s[98:99]


; #define PG8_STAGE(bufoff, gbase, voff) do { _Pragma("unroll") for (int _i = 0; _i < 2; ++_i) \
;         __builtin_amdgcn_global_load_lds((const unsigned*)((const char*)(gbase) + (voff)[_i]), (PG8_LAS unsigned*)(lds + (bufoff) + ldsw + _i * 8192), 16, 0, 0); } while (0)
; #define PG8_LDA(dst, b, h) do { _Pragma("unroll") for (int m = 0; m < 4; ++m) _Pragma("unroll") for (int k = 0; k < 2; ++k) dst[m][k] = *(const PG8_LAS bf16x8*)(lds + PG8_SA(b, h) + aoff + m * 2048 + k * 1024); } while (0)
; #define PG8_LDB(dst, b, h) do { _Pragma("unroll") for (int n = 0; n < 2; ++n) _Pragma("unroll") for (int k = 0; k < 2; ++k) dst[n][k] = *(const PG8_LAS bf16x8*)(lds + PG8_SB(b, h) + boff + n * 2048 + k * 1024); } while (0)
; template <class Epi, class Sched, bool ALIGN_EPI = false, bool SP2 = false>
; __device__ __forceinline__ void gemm_phase(PG8_LAS unsigned char* lds, const Gemm g, const Sched& S, const Epi& E) {
;     ...
;             PG8_WAIT_V(8); PG8_WAIT_L(0); PG8_BAR; PG8_MMA(1, 0, At, B0); PG8_MMA(1, 1, At, B1); PG8_BAR; PG8_SCHED;
;             } else {
;             PG8_LDB(B0, 0, 0); PG8_SCHED; PG8_LDA(At, 0, 0); PG8_STAGE(PG8_SA(1, 1), a1 + hstep, voffA);
;             PG8_WAIT_L(8); PG8_BAR; PG8_WAIT_L(0); PG8_MMA(0, 0, At, B0); PG8_BAR; PG8_SCHED;
;             PG8_LDB(B1, 0, 1); PG8_STAGE(PG8_SB(0, 0), b2, voffB);
;             PG8_BAR; PG8_WAIT_L(0); PG8_MMA(0, 1, At, B1); PG8_BAR;
;             PG8_LDA(At, 0, 1); PG8_STAGE(PG8_SA(0, 0), a2, voffA);
;             PG8_BAR; PG8_WAIT_L(0); PG8_MMA(1, 0, At, B0); PG8_BAR; PG8_SCHED;
;             PG8_STAGE(PG8_SB(0, 1), b2 + hstep, voffB);
;             PG8_WAIT_V(6); PG8_BAR; PG8_MMA(1, 1, At, B1); PG8_BAR;
;             PG8_LDB(B0, 1, 0); PG8_SCHED; PG8_LDA(At, 1, 0); PG8_STAGE(PG8_SA(0, 1), a2 + hstep, voffA);
;             PG8_WAIT_L(8); PG8_BAR; PG8_WAIT_L(0); PG8_MMA(0, 0, At, B0); PG8_BAR; PG8_SCHED;
;             PG8_LDB(B1, 1, 1); PG8_STAGE(PG8_SB(1, 0), b3, voffB);
;             PG8_BAR; PG8_WAIT_L(0); PG8_MMA(0, 1, At, B1); PG8_BAR;
;             PG8_LDA(At, 1, 1); PG8_STAGE(PG8_SA(1, 0), a3, voffA);
;             PG8_BAR; PG8_WAIT_L(0); PG8_MMA(1, 0, At, B0); PG8_BAR; PG8_SCHED;
;             PG8_STAGE(PG8_SB(1, 1), b3 + hstep, voffB);
;             PG8_WAIT_V(6); PG8_BAR; PG8_MMA(1, 1, At, B1); PG8_BAR;
;             }
;         }
;         if constexpr (ALIGN_EPI) { if (wr == 0) PG8_BAR; }
	s_add_i32 s75, s75, 2
	s_add_u32 s70, s70, 0x100
	s_addc_u32 s71, s71, 0
	s_add_u32 s73, s73, 0x100
	s_addc_u32 s74, s74, 0
	s_waitcnt vmcnt(8)
	s_waitcnt lgkmcnt(0)
	s_barrier
	v_mfma_f32_16x16x32_bf16 v[60:63], v[144:147], v[180:183], v[60:63]
	v_mfma_f32_16x16x32_bf16 v[52:55], v[152:155], v[180:183], v[52:55]
	v_mfma_f32_16x16x32_bf16 v[44:47], v[144:147], v[188:191], v[44:47]
	v_mfma_f32_16x16x32_bf16 v[36:39], v[152:155], v[188:191], v[36:39]
	v_mfma_f32_16x16x32_bf16 v[28:31], v[144:147], v[196:199], v[28:31]
	v_mfma_f32_16x16x32_bf16 v[20:23], v[152:155], v[196:199], v[20:23]
	v_mfma_f32_16x16x32_bf16 v[12:15], v[144:147], v[226:229], v[12:15]
	v_mfma_f32_16x16x32_bf16 v[4:7], v[152:155], v[226:229], v[4:7]
	v_mfma_f32_16x16x32_bf16 v[60:63], v[148:151], v[184:187], v[60:63]
	v_mfma_f32_16x16x32_bf16 v[52:55], v[156:159], v[184:187], v[52:55]
	v_mfma_f32_16x16x32_bf16 v[44:47], v[148:151], v[192:195], v[44:47]
	v_mfma_f32_16x16x32_bf16 v[36:39], v[156:159], v[192:195], v[36:39]
	v_mfma_f32_16x16x32_bf16 v[28:31], v[148:151], v[222:225], v[28:31]
	v_mfma_f32_16x16x32_bf16 v[20:23], v[156:159], v[222:225], v[20:23]
	v_mfma_f32_16x16x32_bf16 v[12:15], v[148:151], v[230:233], v[12:15]
	v_mfma_f32_16x16x32_bf16 v[4:7], v[156:159], v[230:233], v[4:7]
	v_mfma_f32_16x16x32_bf16 v[56:59], v[164:167], v[180:183], v[56:59]
	v_mfma_f32_16x16x32_bf16 v[48:51], v[172:175], v[180:183], v[48:51]
	v_mfma_f32_16x16x32_bf16 v[40:43], v[164:167], v[188:191], v[40:43]
	v_mfma_f32_16x16x32_bf16 v[32:35], v[172:175], v[188:191], v[32:35]
	v_mfma_f32_16x16x32_bf16 v[24:27], v[164:167], v[196:199], v[24:27]
	v_mfma_f32_16x16x32_bf16 v[16:19], v[172:175], v[196:199], v[16:19]
	v_mfma_f32_16x16x32_bf16 v[8:11], v[164:167], v[226:229], v[8:11]
	v_mfma_f32_16x16x32_bf16 v[0:3], v[172:175], v[226:229], v[0:3]
	v_mfma_f32_16x16x32_bf16 v[56:59], v[168:171], v[184:187], v[56:59]
	v_mfma_f32_16x16x32_bf16 v[48:51], v[176:179], v[184:187], v[48:51]
	v_mfma_f32_16x16x32_bf16 v[40:43], v[168:171], v[192:195], v[40:43]
	v_mfma_f32_16x16x32_bf16 v[32:35], v[176:179], v[192:195], v[32:35]
	v_mfma_f32_16x16x32_bf16 v[24:27], v[168:171], v[222:225], v[24:27]
	v_mfma_f32_16x16x32_bf16 v[16:19], v[176:179], v[222:225], v[16:19]
	v_mfma_f32_16x16x32_bf16 v[8:11], v[168:171], v[230:233], v[8:11]
	v_mfma_f32_16x16x32_bf16 v[0:3], v[176:179], v[230:233], v[0:3]
	s_barrier
	s_cmp_gt_u32 s75, 29
	s_cbranch_scc0 .LBB0_849
	s_and_b64 vcc, exec, s[8:9]
	s_cbranch_vccz .LBB0_852
	s_barrier
